# nt (streaming) hint on the P0 f32 weight-source loads and adaLN weight loads, read exactly once (on top of v33)
# baseline (speedup 1.0000x reference)
.LBB0_91:
	s_add_i32 s2, s16, s17
	s_add_i32 s3, s2, 0x11000
	v_mov_b32_e32 v25, s3
	s_add_i32 s17, s17, 64
	v_add_co_u32_e32 v26, vcc, 0xfffb8000, v4
	s_nop 1
	v_addc_co_u32_e32 v27, vcc, -1, v5, vcc
	global_load_dwordx4 v[32:35], v[26:27], off nt
	v_add_co_u32_e32 v28, vcc, 0xfffc1000, v4
	s_nop 1
	v_addc_co_u32_e32 v29, vcc, -1, v5, vcc
	global_load_dwordx4 v[36:39], v[28:29], off nt
	v_add_co_u32_e32 v26, vcc, 0xfffca000, v4
	s_nop 1
	v_addc_co_u32_e32 v27, vcc, -1, v5, vcc
	global_load_dwordx4 v[40:43], v[26:27], off nt
	v_add_co_u32_e32 v28, vcc, 0xfffd3000, v4
	s_nop 1
	v_addc_co_u32_e32 v29, vcc, -1, v5, vcc
	global_load_dwordx4 v[44:47], v[28:29], off nt
	v_add_co_u32_e32 v26, vcc, 0xfffdc000, v4
	s_nop 1
	v_addc_co_u32_e32 v27, vcc, -1, v5, vcc
	global_load_dwordx4 v[48:51], v[26:27], off nt
	v_add_co_u32_e32 v28, vcc, 0xfffe5000, v4
	s_nop 1
	v_addc_co_u32_e32 v29, vcc, -1, v5, vcc
	global_load_dwordx4 v[52:55], v[28:29], off nt
	v_add_co_u32_e32 v26, vcc, 0xfffee000, v4
	s_nop 1
	v_addc_co_u32_e32 v27, vcc, -1, v5, vcc
	global_load_dwordx4 v[56:59], v[26:27], off nt
	v_add_co_u32_e32 v28, vcc, 0xffff7000, v4
	s_nop 1
	v_addc_co_u32_e32 v29, vcc, -1, v5, vcc
	global_load_dwordx4 v[60:63], v[28:29], off nt
	global_load_dwordx4 v[64:67], v[4:5], off nt
	v_add_co_u32_e32 v28, vcc, 0x9000, v4
	s_nop 1
	v_addc_co_u32_e32 v29, vcc, 0, v5, vcc
	global_load_dwordx4 v[68:71], v[28:29], off nt
	v_add_co_u32_e32 v26, vcc, 0x12000, v4
	s_nop 1
	v_addc_co_u32_e32 v27, vcc, 0, v5, vcc
	global_load_dwordx4 v[72:75], v[26:27], off nt
	v_add_co_u32_e32 v28, vcc, 0x1b000, v4
	s_nop 1
	v_addc_co_u32_e32 v29, vcc, 0, v5, vcc
	global_load_dwordx4 v[76:79], v[28:29], off nt
	v_add_co_u32_e32 v26, vcc, 0x24000, v4
	s_nop 1
	v_addc_co_u32_e32 v27, vcc, 0, v5, vcc
	global_load_dwordx4 v[80:83], v[26:27], off nt
	v_add_co_u32_e32 v28, vcc, 0x2d000, v4
	s_nop 1
	v_addc_co_u32_e32 v29, vcc, 0, v5, vcc
	global_load_dwordx4 v[84:87], v[28:29], off nt
	v_add_co_u32_e32 v26, vcc, 0x36000, v4
	s_nop 1
	v_addc_co_u32_e32 v27, vcc, 0, v5, vcc
	global_load_dwordx4 v[88:91], v[26:27], off nt
	v_add_co_u32_e32 v28, vcc, 0x3f000, v4
	s_nop 1
	v_addc_co_u32_e32 v29, vcc, 0, v5, vcc
	global_load_dwordx4 v[92:95], v[28:29], off nt
	ds_read_b128 v[136:139], v25
	ds_read_b128 v[152:155], v25 offset:4096
	ds_read_b128 v[168:171], v25 offset:8192
	ds_read_b128 v[140:143], v25 offset:16
	ds_read_b128 v[156:159], v25 offset:4112
	ds_read_b128 v[172:175], v25 offset:8208
	ds_read_b128 v[144:147], v25 offset:32
	ds_read_b128 v[160:163], v25 offset:4128
	ds_read_b128 v[176:179], v25 offset:8224
	ds_read_b128 v[148:151], v25 offset:48
	ds_read_b128 v[164:167], v25 offset:4144
	ds_read_b128 v[180:183], v25 offset:8240
	s_mov_b64 s[2:3], 0x90000
	s_waitcnt lgkmcnt(0)
	s_waitcnt vmcnt(15)
	v_pk_fma_f32 v[8:9], v[32:33], v[136:137], v[8:9] op_sel_hi:[1,0,1]
	v_pk_fma_f32 v[6:7], v[34:35], v[136:137], v[6:7] op_sel_hi:[1,0,1]
	v_pk_fma_f32 v[14:15], v[32:33], v[152:153], v[14:15] op_sel_hi:[1,0,1]
	v_pk_fma_f32 v[10:11], v[34:35], v[152:153], v[10:11] op_sel_hi:[1,0,1]
	v_pk_fma_f32 v[16:17], v[32:33], v[168:169], v[16:17] op_sel_hi:[1,0,1]
	v_pk_fma_f32 v[12:13], v[34:35], v[168:169], v[12:13] op_sel_hi:[1,0,1]
	s_waitcnt vmcnt(14)
	v_pk_fma_f32 v[8:9], v[36:37], v[136:137], v[8:9] op_sel:[0,1,0]
	v_pk_fma_f32 v[6:7], v[38:39], v[136:137], v[6:7] op_sel:[0,1,0]
	v_pk_fma_f32 v[14:15], v[36:37], v[152:153], v[14:15] op_sel:[0,1,0]
	v_pk_fma_f32 v[10:11], v[38:39], v[152:153], v[10:11] op_sel:[0,1,0]
	v_pk_fma_f32 v[16:17], v[36:37], v[168:169], v[16:17] op_sel:[0,1,0]
	v_pk_fma_f32 v[12:13], v[38:39], v[168:169], v[12:13] op_sel:[0,1,0]
	s_waitcnt vmcnt(13)
	v_pk_fma_f32 v[8:9], v[40:41], v[138:139], v[8:9] op_sel_hi:[1,0,1]
	v_pk_fma_f32 v[6:7], v[42:43], v[138:139], v[6:7] op_sel_hi:[1,0,1]
	v_pk_fma_f32 v[14:15], v[40:41], v[154:155], v[14:15] op_sel_hi:[1,0,1]
	v_pk_fma_f32 v[10:11], v[42:43], v[154:155], v[10:11] op_sel_hi:[1,0,1]
	v_pk_fma_f32 v[16:17], v[40:41], v[170:171], v[16:17] op_sel_hi:[1,0,1]
	v_pk_fma_f32 v[12:13], v[42:43], v[170:171], v[12:13] op_sel_hi:[1,0,1]
	s_waitcnt vmcnt(12)
	v_pk_fma_f32 v[8:9], v[44:45], v[138:139], v[8:9] op_sel:[0,1,0]
	v_pk_fma_f32 v[6:7], v[46:47], v[138:139], v[6:7] op_sel:[0,1,0]
	v_pk_fma_f32 v[14:15], v[44:45], v[154:155], v[14:15] op_sel:[0,1,0]
	v_pk_fma_f32 v[10:11], v[46:47], v[154:155], v[10:11] op_sel:[0,1,0]
	v_pk_fma_f32 v[16:17], v[44:45], v[170:171], v[16:17] op_sel:[0,1,0]
	v_pk_fma_f32 v[12:13], v[46:47], v[170:171], v[12:13] op_sel:[0,1,0]
	s_waitcnt vmcnt(11)
	v_pk_fma_f32 v[8:9], v[48:49], v[140:141], v[8:9] op_sel_hi:[1,0,1]
	v_pk_fma_f32 v[6:7], v[50:51], v[140:141], v[6:7] op_sel_hi:[1,0,1]
	v_pk_fma_f32 v[14:15], v[48:49], v[156:157], v[14:15] op_sel_hi:[1,0,1]
	v_pk_fma_f32 v[10:11], v[50:51], v[156:157], v[10:11] op_sel_hi:[1,0,1]
	v_pk_fma_f32 v[16:17], v[48:49], v[172:173], v[16:17] op_sel_hi:[1,0,1]
	v_pk_fma_f32 v[12:13], v[50:51], v[172:173], v[12:13] op_sel_hi:[1,0,1]
	s_waitcnt vmcnt(10)
	v_pk_fma_f32 v[8:9], v[52:53], v[140:141], v[8:9] op_sel:[0,1,0]
	v_pk_fma_f32 v[6:7], v[54:55], v[140:141], v[6:7] op_sel:[0,1,0]
	v_pk_fma_f32 v[14:15], v[52:53], v[156:157], v[14:15] op_sel:[0,1,0]
	v_pk_fma_f32 v[10:11], v[54:55], v[156:157], v[10:11] op_sel:[0,1,0]
	v_pk_fma_f32 v[16:17], v[52:53], v[172:173], v[16:17] op_sel:[0,1,0]
	v_pk_fma_f32 v[12:13], v[54:55], v[172:173], v[12:13] op_sel:[0,1,0]
	s_waitcnt vmcnt(9)
	v_pk_fma_f32 v[8:9], v[56:57], v[142:143], v[8:9] op_sel_hi:[1,0,1]
	v_pk_fma_f32 v[6:7], v[58:59], v[142:143], v[6:7] op_sel_hi:[1,0,1]
	v_pk_fma_f32 v[14:15], v[56:57], v[158:159], v[14:15] op_sel_hi:[1,0,1]
	v_pk_fma_f32 v[10:11], v[58:59], v[158:159], v[10:11] op_sel_hi:[1,0,1]
	v_pk_fma_f32 v[16:17], v[56:57], v[174:175], v[16:17] op_sel_hi:[1,0,1]
	v_pk_fma_f32 v[12:13], v[58:59], v[174:175], v[12:13] op_sel_hi:[1,0,1]
	s_waitcnt vmcnt(8)
	v_pk_fma_f32 v[8:9], v[60:61], v[142:143], v[8:9] op_sel:[0,1,0]
	v_pk_fma_f32 v[6:7], v[62:63], v[142:143], v[6:7] op_sel:[0,1,0]
	v_pk_fma_f32 v[14:15], v[60:61], v[158:159], v[14:15] op_sel:[0,1,0]
	v_pk_fma_f32 v[10:11], v[62:63], v[158:159], v[10:11] op_sel:[0,1,0]
	v_pk_fma_f32 v[16:17], v[60:61], v[174:175], v[16:17] op_sel:[0,1,0]
	v_pk_fma_f32 v[12:13], v[62:63], v[174:175], v[12:13] op_sel:[0,1,0]
	s_waitcnt vmcnt(7)
	v_pk_fma_f32 v[8:9], v[64:65], v[144:145], v[8:9] op_sel_hi:[1,0,1]
	v_pk_fma_f32 v[6:7], v[66:67], v[144:145], v[6:7] op_sel_hi:[1,0,1]
	v_pk_fma_f32 v[14:15], v[64:65], v[160:161], v[14:15] op_sel_hi:[1,0,1]
	v_pk_fma_f32 v[10:11], v[66:67], v[160:161], v[10:11] op_sel_hi:[1,0,1]
	v_pk_fma_f32 v[16:17], v[64:65], v[176:177], v[16:17] op_sel_hi:[1,0,1]
	v_pk_fma_f32 v[12:13], v[66:67], v[176:177], v[12:13] op_sel_hi:[1,0,1]
	s_waitcnt vmcnt(6)
	v_pk_fma_f32 v[8:9], v[68:69], v[144:145], v[8:9] op_sel:[0,1,0]
	v_pk_fma_f32 v[6:7], v[70:71], v[144:145], v[6:7] op_sel:[0,1,0]
	v_pk_fma_f32 v[14:15], v[68:69], v[160:161], v[14:15] op_sel:[0,1,0]
	v_pk_fma_f32 v[10:11], v[70:71], v[160:161], v[10:11] op_sel:[0,1,0]
	v_pk_fma_f32 v[16:17], v[68:69], v[176:177], v[16:17] op_sel:[0,1,0]
	v_pk_fma_f32 v[12:13], v[70:71], v[176:177], v[12:13] op_sel:[0,1,0]
	s_waitcnt vmcnt(5)
	v_pk_fma_f32 v[8:9], v[72:73], v[146:147], v[8:9] op_sel_hi:[1,0,1]
	v_pk_fma_f32 v[6:7], v[74:75], v[146:147], v[6:7] op_sel_hi:[1,0,1]
	v_pk_fma_f32 v[14:15], v[72:73], v[162:163], v[14:15] op_sel_hi:[1,0,1]
	v_pk_fma_f32 v[10:11], v[74:75], v[162:163], v[10:11] op_sel_hi:[1,0,1]
	v_pk_fma_f32 v[16:17], v[72:73], v[178:179], v[16:17] op_sel_hi:[1,0,1]
	v_pk_fma_f32 v[12:13], v[74:75], v[178:179], v[12:13] op_sel_hi:[1,0,1]
	s_waitcnt vmcnt(4)
	v_pk_fma_f32 v[8:9], v[76:77], v[146:147], v[8:9] op_sel:[0,1,0]
	v_pk_fma_f32 v[6:7], v[78:79], v[146:147], v[6:7] op_sel:[0,1,0]
	v_pk_fma_f32 v[14:15], v[76:77], v[162:163], v[14:15] op_sel:[0,1,0]
	v_pk_fma_f32 v[10:11], v[78:79], v[162:163], v[10:11] op_sel:[0,1,0]
	v_pk_fma_f32 v[16:17], v[76:77], v[178:179], v[16:17] op_sel:[0,1,0]
	v_pk_fma_f32 v[12:13], v[78:79], v[178:179], v[12:13] op_sel:[0,1,0]
	s_waitcnt vmcnt(3)
	v_pk_fma_f32 v[8:9], v[80:81], v[148:149], v[8:9] op_sel_hi:[1,0,1]
	v_pk_fma_f32 v[6:7], v[82:83], v[148:149], v[6:7] op_sel_hi:[1,0,1]
	v_pk_fma_f32 v[14:15], v[80:81], v[164:165], v[14:15] op_sel_hi:[1,0,1]
	v_pk_fma_f32 v[10:11], v[82:83], v[164:165], v[10:11] op_sel_hi:[1,0,1]
	v_pk_fma_f32 v[16:17], v[80:81], v[180:181], v[16:17] op_sel_hi:[1,0,1]
	v_pk_fma_f32 v[12:13], v[82:83], v[180:181], v[12:13] op_sel_hi:[1,0,1]
	s_waitcnt vmcnt(2)
	v_pk_fma_f32 v[8:9], v[84:85], v[148:149], v[8:9] op_sel:[0,1,0]
	v_pk_fma_f32 v[6:7], v[86:87], v[148:149], v[6:7] op_sel:[0,1,0]
	v_pk_fma_f32 v[14:15], v[84:85], v[164:165], v[14:15] op_sel:[0,1,0]
	v_pk_fma_f32 v[10:11], v[86:87], v[164:165], v[10:11] op_sel:[0,1,0]
	v_pk_fma_f32 v[16:17], v[84:85], v[180:181], v[16:17] op_sel:[0,1,0]
	v_pk_fma_f32 v[12:13], v[86:87], v[180:181], v[12:13] op_sel:[0,1,0]
	s_waitcnt vmcnt(1)
	v_pk_fma_f32 v[8:9], v[88:89], v[150:151], v[8:9] op_sel_hi:[1,0,1]
	v_pk_fma_f32 v[6:7], v[90:91], v[150:151], v[6:7] op_sel_hi:[1,0,1]
	v_pk_fma_f32 v[14:15], v[88:89], v[166:167], v[14:15] op_sel_hi:[1,0,1]
	v_pk_fma_f32 v[10:11], v[90:91], v[166:167], v[10:11] op_sel_hi:[1,0,1]
	v_pk_fma_f32 v[16:17], v[88:89], v[182:183], v[16:17] op_sel_hi:[1,0,1]
	v_pk_fma_f32 v[12:13], v[90:91], v[182:183], v[12:13] op_sel_hi:[1,0,1]
	s_waitcnt vmcnt(0)
	v_pk_fma_f32 v[8:9], v[92:93], v[150:151], v[8:9] op_sel:[0,1,0]
	v_pk_fma_f32 v[6:7], v[94:95], v[150:151], v[6:7] op_sel:[0,1,0]
	v_pk_fma_f32 v[14:15], v[92:93], v[166:167], v[14:15] op_sel:[0,1,0]
	v_pk_fma_f32 v[10:11], v[94:95], v[166:167], v[10:11] op_sel:[0,1,0]
	v_pk_fma_f32 v[16:17], v[92:93], v[182:183], v[16:17] op_sel:[0,1,0]
	v_pk_fma_f32 v[12:13], v[94:95], v[182:183], v[12:13] op_sel:[0,1,0]
	v_lshl_add_u64 v[4:5], v[4:5], 0, s[2:3]
	s_cmpk_eq_i32 s17, 0x100
	s_cbranch_scc0 .LBB0_91
	s_and_b32 s2, s14, 15
	s_cmp_eq_u32 s2, 0
	s_cbranch_scc0 .LBB0_89
	v_readlane_b32 s68, v249, 2
	v_readlane_b32 s78, v249, 12
	v_readlane_b32 s79, v249, 13
	s_mul_i32 s2, s15, 0x9000
	s_mov_b64 s[18:19], s[78:79]
	s_mul_hi_i32 s3, s15, 0x9000
	s_add_u32 s2, s18, s2
	s_addc_u32 s3, s19, s3
	v_lshl_add_u64 v[4:5], v[2:3], 2, s[2:3]
	global_load_dwordx4 v[26:29], v[4:5], off
	v_readlane_b32 s69, v249, 3
	v_readlane_b32 s70, v249, 4
	v_readlane_b32 s71, v249, 5
	v_readlane_b32 s72, v249, 6
	v_readlane_b32 s73, v249, 7
	v_readlane_b32 s74, v249, 8
	v_readlane_b32 s75, v249, 9
	v_readlane_b32 s76, v249, 10
	v_readlane_b32 s77, v249, 11
	v_readlane_b32 s80, v249, 14
	v_readlane_b32 s81, v249, 15
	v_readlane_b32 s82, v249, 16
	v_readlane_b32 s83, v249, 17
	s_waitcnt vmcnt(0)
	v_pk_add_f32 v[6:7], v[6:7], v[28:29]
	v_pk_add_f32 v[8:9], v[8:9], v[26:27]
	v_pk_add_f32 v[10:11], v[10:11], v[28:29]
	v_pk_add_f32 v[14:15], v[14:15], v[26:27]
	v_pk_add_f32 v[12:13], v[12:13], v[28:29]
	v_pk_add_f32 v[16:17], v[16:17], v[26:27]
	s_branch .LBB0_89

.LBB0_102:
	s_mov_b64 s[2:3], 0
	s_andn2_b64 vcc, exec, s[18:19]
	s_mov_b64 s[18:19], 0
	s_cbranch_vccnz .LBB0_104
	s_mul_i32 s16, s8, 0x4f00
	s_sub_i32 s16, s26, s16
	s_mul_i32 s17, s25, 0x580000
	v_readlane_b32 s19, v249, 62
	s_mul_hi_u32 s18, s25, 0x580000
	s_add_u32 s17, s19, s17
	v_readlane_b32 s19, v249, 63
	v_readlane_b32 s68, v249, 18
	s_addc_u32 s18, s19, s18
	v_readlane_b32 s70, v249, 20
	v_readlane_b32 s71, v249, 21
	s_add_u32 s24, s70, s1
	s_addc_u32 vcc_hi, s71, s0
	s_and_b32 s19, s16, 0x1ffc0
	s_and_b32 s16, s27, 0x3e0
	s_add_i32 s28, s23, 0xfffff500
	s_lshl_b32 vcc_lo, s16, 2
	s_add_u32 vcc_lo, s24, vcc_lo
	v_or_b32_e32 v4, s19, v128
	s_addc_u32 vcc_hi, vcc_hi, 0
	v_lshl_add_u64 v[2:3], vcc, 0, v[130:131]
	v_lshlrev_b32_e32 v4, 12, v4
	v_mov_b32_e32 v5, v131
	v_lshl_add_u64 v[2:3], v[2:3], 0, v[4:5]
	s_movk_i32 s24, 0x2000
	v_add_co_u32_e32 v4, vcc, s24, v2
	global_load_dword v6, v[2:3], off nt
	s_nop 0
	v_addc_co_u32_e32 v5, vcc, 0, v3, vcc
	global_load_dword v7, v[4:5], off nt
	v_add_co_u32_e32 v4, vcc, s40, v2
	s_movk_i32 s24, 0x6000
	s_nop 0
	v_addc_co_u32_e32 v5, vcc, 0, v3, vcc
	global_load_dword v8, v[4:5], off nt
	v_add_co_u32_e32 v4, vcc, s24, v2
	s_mov_b32 s24, 0x8000
	s_nop 0
	v_addc_co_u32_e32 v5, vcc, 0, v3, vcc
	global_load_dword v9, v[4:5], off nt
	v_add_co_u32_e32 v4, vcc, s24, v2
	s_mov_b32 s24, 0xa000
	s_nop 0
	v_addc_co_u32_e32 v5, vcc, 0, v3, vcc
	global_load_dword v10, v[4:5], off nt
	v_add_co_u32_e32 v4, vcc, s24, v2
	s_mov_b32 s24, 0xc000
	s_nop 0
	v_addc_co_u32_e32 v5, vcc, 0, v3, vcc
	global_load_dword v11, v[4:5], off nt
	v_add_co_u32_e32 v4, vcc, s24, v2
	s_mov_b32 s24, 0xe000
	s_nop 0
	v_addc_co_u32_e32 v5, vcc, 0, v3, vcc
	global_load_dword v12, v[4:5], off nt
	v_add_co_u32_e32 v4, vcc, s24, v2
	s_mov_b32 s24, 0x14000
	s_nop 0
	v_addc_co_u32_e32 v5, vcc, 0, v3, vcc
	global_load_dword v13, v[4:5], off nt
	v_add_co_u32_e32 v4, vcc, s46, v2
	s_lshl_b32 s19, s19, 1
	s_nop 0
	v_addc_co_u32_e32 v5, vcc, 0, v3, vcc
	global_load_dword v14, v[4:5], off nt
	v_add_co_u32_e32 v4, vcc, s31, v2
	v_readlane_b32 s69, v249, 19
	s_nop 0
	v_addc_co_u32_e32 v5, vcc, 0, v3, vcc
	global_load_dword v15, v[4:5], off nt
	v_add_co_u32_e32 v4, vcc, s24, v2
	s_mov_b32 s24, 0x18000
	s_nop 0
	v_addc_co_u32_e32 v5, vcc, 0, v3, vcc
	global_load_dword v16, v[4:5], off nt
	v_add_co_u32_e32 v4, vcc, s48, v2
	v_readlane_b32 s72, v249, 22
	s_nop 0
	v_addc_co_u32_e32 v5, vcc, 0, v3, vcc
	global_load_dword v17, v[4:5], off nt
	v_add_co_u32_e32 v4, vcc, s24, v2
	s_mov_b32 s24, 0x1a000
	s_nop 0
	v_addc_co_u32_e32 v5, vcc, 0, v3, vcc
	global_load_dword v25, v[4:5], off nt
	v_add_co_u32_e32 v4, vcc, s24, v2
	s_mov_b32 s24, 0x1c000
	s_nop 0
	v_addc_co_u32_e32 v5, vcc, 0, v3, vcc
	global_load_dword v26, v[4:5], off nt
	v_add_co_u32_e32 v4, vcc, s24, v2
	s_mov_b32 s24, 0x1e000
	s_nop 0
	v_addc_co_u32_e32 v5, vcc, 0, v3, vcc
	global_load_dword v27, v[4:5], off nt
	v_add_co_u32_e32 v4, vcc, s24, v2
	s_mov_b32 s24, 0x20000
	s_nop 0
	v_addc_co_u32_e32 v5, vcc, 0, v3, vcc
	global_load_dword v28, v[4:5], off nt
	v_add_co_u32_e32 v4, vcc, s24, v2
	v_readlane_b32 s73, v249, 23
	s_nop 0
	v_addc_co_u32_e32 v5, vcc, 0, v3, vcc
	global_load_dword v29, v[4:5], off nt
	v_add_co_u32_e32 v4, vcc, s54, v2
	v_readlane_b32 s74, v249, 24
	s_nop 0
	v_addc_co_u32_e32 v5, vcc, 0, v3, vcc
	global_load_dword v30, v[4:5], off nt
	v_add_co_u32_e32 v4, vcc, s35, v2
	v_readlane_b32 s75, v249, 25
	s_nop 0
	v_addc_co_u32_e32 v5, vcc, 0, v3, vcc
	global_load_dword v31, v[4:5], off nt
	v_add_co_u32_e32 v4, vcc, s55, v2
	v_readlane_b32 s76, v249, 26
	s_nop 0
	v_addc_co_u32_e32 v5, vcc, 0, v3, vcc
	global_load_dword v32, v[4:5], off nt
	v_add_co_u32_e32 v4, vcc, s56, v2
	v_readlane_b32 s77, v249, 27
	s_nop 0
	v_addc_co_u32_e32 v5, vcc, 0, v3, vcc
	global_load_dword v33, v[4:5], off nt
	v_add_co_u32_e32 v4, vcc, s57, v2
	v_readlane_b32 s78, v249, 28
	s_nop 0
	v_addc_co_u32_e32 v5, vcc, 0, v3, vcc
	global_load_dword v34, v[4:5], off nt
	v_add_co_u32_e32 v4, vcc, s58, v2
	v_readlane_b32 s79, v249, 29
	s_nop 0
	v_addc_co_u32_e32 v5, vcc, 0, v3, vcc
	global_load_dword v35, v[4:5], off nt
	v_add_co_u32_e32 v4, vcc, s59, v2
	v_readlane_b32 s80, v249, 30
	s_nop 0
	v_addc_co_u32_e32 v5, vcc, 0, v3, vcc
	global_load_dword v36, v[4:5], off nt
	v_add_co_u32_e32 v4, vcc, s60, v2
	v_readlane_b32 s81, v249, 31
	s_nop 0
	v_addc_co_u32_e32 v5, vcc, 0, v3, vcc
	global_load_dword v37, v[4:5], off nt
	v_add_co_u32_e32 v4, vcc, s61, v2
	v_readlane_b32 s82, v249, 32
	s_nop 0
	v_addc_co_u32_e32 v5, vcc, 0, v3, vcc
	global_load_dword v38, v[4:5], off nt
	v_add_co_u32_e32 v4, vcc, s62, v2
	v_readlane_b32 s83, v249, 33
	s_nop 0
	v_addc_co_u32_e32 v5, vcc, 0, v3, vcc
	global_load_dword v39, v[4:5], off nt
	v_add_co_u32_e32 v4, vcc, s37, v2
	s_nop 1
	v_addc_co_u32_e32 v5, vcc, 0, v3, vcc
	global_load_dword v40, v[4:5], off nt
	v_add_co_u32_e32 v4, vcc, s63, v2
	s_nop 1
	v_addc_co_u32_e32 v5, vcc, 0, v3, vcc
	global_load_dword v41, v[4:5], off nt
	v_add_co_u32_e32 v4, vcc, s64, v2
	s_nop 1
	v_addc_co_u32_e32 v5, vcc, 0, v3, vcc
	global_load_dword v42, v[4:5], off nt
	v_add_co_u32_e32 v4, vcc, s65, v2
	s_nop 1
	v_addc_co_u32_e32 v5, vcc, 0, v3, vcc
	v_add_co_u32_e32 v2, vcc, s66, v2
	global_load_dword v4, v[4:5], off nt
	s_nop 0
	v_addc_co_u32_e32 v3, vcc, 0, v3, vcc
	global_load_dword v2, v[2:3], off nt
	v_add_u32_e32 v3, 0x400, v18
	s_waitcnt vmcnt(30)
	ds_write2_b32 v18, v6, v7 offset1:66
	s_waitcnt vmcnt(28)
	ds_write2_b32 v18, v8, v9 offset0:132 offset1:198
	s_waitcnt vmcnt(26)
	ds_write2_b32 v3, v10, v11 offset0:8 offset1:74
	s_waitcnt vmcnt(24)
	ds_write2_b32 v3, v12, v13 offset0:140 offset1:206
	v_add_u32_e32 v3, 0x800, v18
	s_waitcnt vmcnt(22)
	ds_write2_b32 v3, v14, v15 offset0:16 offset1:82
	s_waitcnt vmcnt(20)
	ds_write2_b32 v3, v16, v17 offset0:148 offset1:214
	v_add_u32_e32 v3, 0xc00, v18
	s_waitcnt vmcnt(18)
	ds_write2_b32 v3, v25, v26 offset0:24 offset1:90
	s_waitcnt vmcnt(16)
	ds_write2_b32 v3, v27, v28 offset0:156 offset1:222
	v_add_u32_e32 v3, 0x1000, v18
	s_waitcnt vmcnt(14)
	ds_write2_b32 v3, v29, v30 offset0:32 offset1:98
	s_waitcnt vmcnt(12)
	ds_write2_b32 v3, v31, v32 offset0:164 offset1:230
	v_add_u32_e32 v3, 0x1400, v18
	s_waitcnt vmcnt(10)
	ds_write2_b32 v3, v33, v34 offset0:40 offset1:106
	s_waitcnt vmcnt(8)
	ds_write2_b32 v3, v35, v36 offset0:172 offset1:238
	v_add_u32_e32 v3, 0x1800, v18
	s_waitcnt vmcnt(6)
	ds_write2_b32 v3, v37, v38 offset0:48 offset1:114
	s_waitcnt vmcnt(4)
	ds_write2_b32 v3, v39, v40 offset0:180 offset1:246
	v_add_u32_e32 v3, 0x1c00, v18
	s_waitcnt vmcnt(2)
	ds_write2_b32 v3, v41, v42 offset0:56 offset1:122
	s_waitcnt vmcnt(0)
	ds_write2_b32 v3, v4, v2 offset0:188 offset1:254
	s_waitcnt lgkmcnt(0)
	ds_read2_b32 v[8:9], v20 offset0:33 offset1:41
	ds_read2_b32 v[10:11], v20 offset1:8
	s_add_u32 vcc_lo, s17, s19
	ds_read2_b32 v[12:13], v20 offset0:66 offset1:74
	ds_read2_b32 v[14:15], v20 offset0:99 offset1:107
	ds_read2_b32 v[16:17], v20 offset0:132 offset1:140
	ds_read2_b32 v[26:27], v20 offset0:165 offset1:173
	ds_read2_b32 v[28:29], v20 offset0:198 offset1:206
	ds_read2_b32 v[30:31], v20 offset0:231 offset1:239
	s_addc_u32 vcc_hi, s18, 0
	v_lshlrev_b32_e32 v2, 1, v0
	v_mov_b32_e32 v3, v131
	v_lshl_add_u64 v[6:7], vcc, 0, v[2:3]
	s_waitcnt lgkmcnt(6)
	v_cvt_pk_bf16_f32 v2, v10, v8
	v_or_b32_e32 v8, s16, v19
	v_mul_u32_u24_e32 v8, 0xb00, v8
	v_lshlrev_b32_e32 v32, 1, v8
	v_mov_b32_e32 v33, v131
	v_or_b32_e32 v8, s16, v21
	s_waitcnt lgkmcnt(4)
	v_cvt_pk_bf16_f32 v3, v12, v14
	s_waitcnt lgkmcnt(2)
	v_cvt_pk_bf16_f32 v4, v16, v26
	s_waitcnt lgkmcnt(0)
	v_cvt_pk_bf16_f32 v5, v28, v30
	v_lshl_add_u64 v[32:33], v[6:7], 0, v[32:33]
	v_mul_u32_u24_e32 v8, 0xb00, v8
	global_store_dwordx4 v[32:33], v[2:5], off
	v_lshlrev_b32_e32 v8, 1, v8
	v_mov_b32_e32 v33, v131
	v_cvt_pk_bf16_f32 v2, v11, v9
	v_mov_b32_e32 v9, v131
	v_cvt_pk_bf16_f32 v3, v13, v15
	v_cvt_pk_bf16_f32 v4, v17, v27
	v_cvt_pk_bf16_f32 v5, v29, v31
	v_lshl_add_u64 v[8:9], v[6:7], 0, v[8:9]
	global_store_dwordx4 v[8:9], v[2:5], off
	ds_read2_b32 v[8:9], v20 offset0:16 offset1:24
	ds_read2_b32 v[10:11], v20 offset0:49 offset1:57
	ds_read2_b32 v[12:13], v20 offset0:82 offset1:90
	ds_read2_b32 v[14:15], v20 offset0:115 offset1:123
	ds_read2_b32 v[16:17], v20 offset0:148 offset1:156
	ds_read2_b32 v[26:27], v20 offset0:181 offset1:189
	ds_read2_b32 v[28:29], v20 offset0:214 offset1:222
	ds_read2_b32 v[30:31], v20 offset0:247 offset1:255
	s_mov_b64 s[18:19], -1
	s_waitcnt lgkmcnt(6)
	v_cvt_pk_bf16_f32 v2, v8, v10
	v_or_b32_e32 v8, s16, v22
	v_mul_u32_u24_e32 v8, 0xb00, v8
	v_lshlrev_b32_e32 v32, 1, v8
	v_or_b32_e32 v8, s16, v23
	s_waitcnt lgkmcnt(4)
	v_cvt_pk_bf16_f32 v3, v12, v14
	s_waitcnt lgkmcnt(2)
	v_cvt_pk_bf16_f32 v4, v16, v26
	s_waitcnt lgkmcnt(0)
	v_cvt_pk_bf16_f32 v5, v28, v30
	v_lshl_add_u64 v[32:33], v[6:7], 0, v[32:33]
	v_mul_u32_u24_e32 v8, 0xb00, v8
	global_store_dwordx4 v[32:33], v[2:5], off
	v_lshlrev_b32_e32 v8, 1, v8
	s_mov_b64 s[16:17], 0
	v_cvt_pk_bf16_f32 v2, v9, v11
	v_mov_b32_e32 v9, v131
	v_cvt_pk_bf16_f32 v3, v13, v15
	v_cvt_pk_bf16_f32 v4, v17, v27
	v_cvt_pk_bf16_f32 v5, v29, v31
	v_lshl_add_u64 v[6:7], v[6:7], 0, v[8:9]
	global_store_dwordx4 v[6:7], v[2:5], off
	s_waitcnt lgkmcnt(0)
.LBB0_104:
	s_andn2_b64 vcc, exec, s[2:3]
	s_cbranch_vccnz .LBB0_106
	s_lshl_b64 s[2:3], s[14:15], 2
	v_readlane_b32 s68, v249, 18
	v_readlane_b32 s69, v249, 19
	s_add_u32 s17, s68, s2
	s_addc_u32 s19, s69, s3
	s_add_i32 s2, s20, 0xfffffa80
	s_mul_i32 s3, s2, 0xba2f
	s_lshr_b32 s18, s3, 16
	s_lshr_b32 s3, s3, 22
	s_mulk_i32 s3, 0x58
	s_sub_i32 s2, s2, s3
	s_and_b32 s16, s2, 0xffff
	s_add_i32 s28, s23, 0xfffffa80
	s_and_b32 s3, s18, 0xffc0
	s_lshl_b32 s2, s16, 5
	s_lshl_b32 s18, s16, 7
	v_or_b32_e32 v4, s3, v128
	s_add_u32 s18, s17, s18
	s_addc_u32 s19, s19, 0
	v_mul_u32_u24_e32 v4, 0xb00, v4
	v_lshl_add_u64 v[2:3], s[18:19], 0, v[130:131]
	v_lshlrev_b32_e32 v4, 2, v4
	v_mov_b32_e32 v5, v131
	v_lshl_add_u64 v[2:3], v[2:3], 0, v[4:5]
	v_add_co_u32_e32 v4, vcc, s67, v2
	global_load_dword v6, v[2:3], off nt
	s_nop 0
	v_addc_co_u32_e32 v5, vcc, 0, v3, vcc
	global_load_dword v7, v[4:5], off offset:2048 nt
	v_add_co_u32_e32 v4, vcc, s6, v2
	s_lshl_b32 s16, s16, 6
	s_nop 0
	v_addc_co_u32_e32 v5, vcc, 0, v3, vcc
	global_load_dword v8, v[4:5], off nt
	v_add_co_u32_e32 v4, vcc, s46, v2
	s_and_b32 s16, s16, 0x1f00
	s_nop 0
	v_addc_co_u32_e32 v5, vcc, 0, v3, vcc
	global_load_dword v9, v[4:5], off offset:2048 nt
	v_add_co_u32_e32 v4, vcc, s48, v2
	s_or_b32 s18, s16, 0x80
	s_nop 0
	v_addc_co_u32_e32 v5, vcc, 0, v3, vcc
	global_load_dword v10, v[4:5], off nt
	v_add_co_u32_e32 v4, vcc, s34, v2
	s_lshl_b32 s3, s3, 1
	s_nop 0
	v_addc_co_u32_e32 v5, vcc, 0, v3, vcc
	global_load_dword v11, v[4:5], off offset:2048 nt
	v_add_co_u32_e32 v4, vcc, s7, v2
	s_add_u32 s16, s21, s3
	s_nop 0
	v_addc_co_u32_e32 v5, vcc, 0, v3, vcc
	global_load_dword v12, v[4:5], off nt
	v_add_co_u32_e32 v4, vcc, s55, v2
	s_addc_u32 s17, s22, 0
	s_nop 0
	v_addc_co_u32_e32 v5, vcc, 0, v3, vcc
	global_load_dword v13, v[4:5], off offset:2048 nt
	v_add_co_u32_e32 v4, vcc, s58, v2
	s_and_b32 s2, s2, 0x60
	s_nop 0
	v_addc_co_u32_e32 v5, vcc, 0, v3, vcc
	global_load_dword v14, v[4:5], off nt
	v_add_co_u32_e32 v4, vcc, s4, v2
	v_readlane_b32 s70, v249, 20
	s_nop 0
	v_addc_co_u32_e32 v5, vcc, 0, v3, vcc
	global_load_dword v15, v[4:5], off offset:2048 nt
	v_add_co_u32_e32 v4, vcc, s5, v2
	v_readlane_b32 s71, v249, 21
	s_nop 0
	v_addc_co_u32_e32 v5, vcc, 0, v3, vcc
	global_load_dword v16, v[4:5], off nt
	v_add_co_u32_e32 v4, vcc, s65, v2
	v_readlane_b32 s72, v249, 22
	s_nop 0
	v_addc_co_u32_e32 v5, vcc, 0, v3, vcc
	global_load_dword v17, v[4:5], off offset:2048 nt
	v_add_co_u32_e32 v4, vcc, s39, v2
	v_readlane_b32 s73, v249, 23
	s_nop 0
	v_addc_co_u32_e32 v5, vcc, 0, v3, vcc
	global_load_dword v25, v[4:5], off nt
	v_add_co_u32_e32 v4, vcc, s41, v2
	v_readlane_b32 s74, v249, 24
	s_nop 0
	v_addc_co_u32_e32 v5, vcc, 0, v3, vcc
	global_load_dword v26, v[4:5], off offset:2048 nt
	v_add_co_u32_e32 v4, vcc, s42, v2
	v_readlane_b32 s75, v249, 25
	s_nop 0
	v_addc_co_u32_e32 v5, vcc, 0, v3, vcc
	global_load_dword v27, v[4:5], off nt
	v_add_co_u32_e32 v4, vcc, s43, v2
	v_readlane_b32 s76, v249, 26
	s_nop 0
	v_addc_co_u32_e32 v5, vcc, 0, v3, vcc
	global_load_dword v28, v[4:5], off offset:2048 nt
	v_add_co_u32_e32 v4, vcc, s44, v2
	v_readlane_b32 s77, v249, 27
	s_nop 0
	v_addc_co_u32_e32 v5, vcc, 0, v3, vcc
	global_load_dword v29, v[4:5], off nt
	v_add_co_u32_e32 v4, vcc, s45, v2
	v_readlane_b32 s78, v249, 28
	s_nop 0
	v_addc_co_u32_e32 v5, vcc, 0, v3, vcc
	global_load_dword v30, v[4:5], off offset:2048 nt
	v_add_co_u32_e32 v4, vcc, s47, v2
	v_readlane_b32 s79, v249, 29
	s_nop 0
	v_addc_co_u32_e32 v5, vcc, 0, v3, vcc
	global_load_dword v31, v[4:5], off nt
	v_add_co_u32_e32 v4, vcc, s49, v2
	v_readlane_b32 s80, v249, 30
	s_nop 0
	v_addc_co_u32_e32 v5, vcc, 0, v3, vcc
	global_load_dword v32, v[4:5], off offset:2048 nt
	v_add_co_u32_e32 v4, vcc, s50, v2
	v_readlane_b32 s81, v249, 31
	s_nop 0
	v_addc_co_u32_e32 v5, vcc, 0, v3, vcc
	global_load_dword v33, v[4:5], off nt
	v_add_co_u32_e32 v4, vcc, s51, v2
	v_readlane_b32 s82, v249, 32
	s_nop 0
	v_addc_co_u32_e32 v5, vcc, 0, v3, vcc
	global_load_dword v34, v[4:5], off offset:2048 nt
	v_add_co_u32_e32 v4, vcc, s52, v2
	v_readlane_b32 s83, v249, 33
	s_nop 0
	v_addc_co_u32_e32 v5, vcc, 0, v3, vcc
	global_load_dword v35, v[4:5], off nt
	v_add_co_u32_e32 v4, vcc, s53, v2
	s_nop 1
	v_addc_co_u32_e32 v5, vcc, 0, v3, vcc
	global_load_dword v36, v[4:5], off offset:2048 nt
	v_add_co_u32_e32 v4, vcc, s84, v2
	s_nop 1
	v_addc_co_u32_e32 v5, vcc, 0, v3, vcc
	global_load_dword v37, v[4:5], off nt
	v_add_co_u32_e32 v4, vcc, s85, v2
	s_nop 1
	v_addc_co_u32_e32 v5, vcc, 0, v3, vcc
	global_load_dword v38, v[4:5], off offset:2048 nt
	v_add_co_u32_e32 v4, vcc, s86, v2
	s_nop 1
	v_addc_co_u32_e32 v5, vcc, 0, v3, vcc
	global_load_dword v39, v[4:5], off nt
	v_add_co_u32_e32 v4, vcc, s87, v2
	s_nop 1
	v_addc_co_u32_e32 v5, vcc, 0, v3, vcc
	global_load_dword v40, v[4:5], off offset:2048 nt
	v_add_co_u32_e32 v4, vcc, s88, v2
	s_nop 1
	v_addc_co_u32_e32 v5, vcc, 0, v3, vcc
	global_load_dword v41, v[4:5], off nt
	v_add_co_u32_e32 v4, vcc, s89, v2
	s_nop 1
	v_addc_co_u32_e32 v5, vcc, 0, v3, vcc
	global_load_dword v42, v[4:5], off offset:2048 nt
	v_add_co_u32_e32 v4, vcc, s90, v2
	s_nop 1
	v_addc_co_u32_e32 v5, vcc, 0, v3, vcc
	v_add_co_u32_e32 v2, vcc, s91, v2
	global_load_dword v4, v[4:5], off nt
	s_nop 0
	v_addc_co_u32_e32 v3, vcc, 0, v3, vcc
	global_load_dword v2, v[2:3], off offset:2048 nt
	v_add_u32_e32 v3, 0x400, v18
	s_waitcnt vmcnt(30)
	ds_write2_b32 v18, v6, v7 offset1:66
	s_waitcnt vmcnt(28)
	ds_write2_b32 v18, v8, v9 offset0:132 offset1:198
	s_waitcnt vmcnt(26)
	ds_write2_b32 v3, v10, v11 offset0:8 offset1:74
	s_waitcnt vmcnt(24)
	ds_write2_b32 v3, v12, v13 offset0:140 offset1:206
	v_add_u32_e32 v3, 0x800, v18
	s_waitcnt vmcnt(22)
	ds_write2_b32 v3, v14, v15 offset0:16 offset1:82
	s_waitcnt vmcnt(20)
	ds_write2_b32 v3, v16, v17 offset0:148 offset1:214
	v_add_u32_e32 v3, 0xc00, v18
	s_waitcnt vmcnt(18)
	ds_write2_b32 v3, v25, v26 offset0:24 offset1:90
	s_waitcnt vmcnt(16)
	ds_write2_b32 v3, v27, v28 offset0:156 offset1:222
	v_add_u32_e32 v3, 0x1000, v18
	s_waitcnt vmcnt(14)
	ds_write2_b32 v3, v29, v30 offset0:32 offset1:98
	s_waitcnt vmcnt(12)
	ds_write2_b32 v3, v31, v32 offset0:164 offset1:230
	v_add_u32_e32 v3, 0x1400, v18
	s_waitcnt vmcnt(10)
	ds_write2_b32 v3, v33, v34 offset0:40 offset1:106
	s_waitcnt vmcnt(8)
	ds_write2_b32 v3, v35, v36 offset0:172 offset1:238
	v_add_u32_e32 v3, 0x1800, v18
	s_waitcnt vmcnt(6)
	ds_write2_b32 v3, v37, v38 offset0:48 offset1:114
	s_waitcnt vmcnt(4)
	ds_write2_b32 v3, v39, v40 offset0:180 offset1:246
	v_add_u32_e32 v3, 0x1c00, v18
	s_waitcnt vmcnt(2)
	ds_write2_b32 v3, v41, v42 offset0:56 offset1:122
	s_waitcnt vmcnt(0)
	ds_write2_b32 v3, v4, v2 offset0:188 offset1:254
	s_waitcnt lgkmcnt(0)
	ds_read2_b32 v[8:9], v20 offset0:33 offset1:41
	ds_read2_b32 v[10:11], v20 offset1:8
	ds_read2_b32 v[12:13], v20 offset0:66 offset1:74
	ds_read2_b32 v[14:15], v20 offset0:99 offset1:107
	ds_read2_b32 v[16:17], v20 offset0:132 offset1:140
	ds_read2_b32 v[26:27], v20 offset0:165 offset1:173
	ds_read2_b32 v[28:29], v20 offset0:198 offset1:206
	ds_read2_b32 v[30:31], v20 offset0:231 offset1:239
	v_lshlrev_b32_e32 v2, 1, v0
	v_mov_b32_e32 v3, v131
	v_lshl_add_u64 v[6:7], s[16:17], 0, v[2:3]
	s_waitcnt lgkmcnt(6)
	v_cvt_pk_bf16_f32 v2, v10, v8
	v_or_b32_e32 v8, s2, v19
	v_or_b32_e32 v8, s18, v8
	v_lshlrev_b32_e32 v32, 11, v8
	v_mov_b32_e32 v33, v131
	v_or_b32_e32 v8, s2, v21
	s_waitcnt lgkmcnt(4)
	v_cvt_pk_bf16_f32 v3, v12, v14
	s_waitcnt lgkmcnt(2)
	v_cvt_pk_bf16_f32 v4, v16, v26
	s_waitcnt lgkmcnt(0)
	v_cvt_pk_bf16_f32 v5, v28, v30
	v_lshl_add_u64 v[32:33], v[6:7], 0, v[32:33]
	v_or_b32_e32 v8, s18, v8
	global_store_dwordx4 v[32:33], v[2:5], off
	v_lshlrev_b32_e32 v8, 11, v8
	v_mov_b32_e32 v33, v131
	v_cvt_pk_bf16_f32 v2, v11, v9
	v_mov_b32_e32 v9, v131
	v_cvt_pk_bf16_f32 v3, v13, v15
	v_cvt_pk_bf16_f32 v4, v17, v27
	v_cvt_pk_bf16_f32 v5, v29, v31
	v_lshl_add_u64 v[8:9], v[6:7], 0, v[8:9]
	global_store_dwordx4 v[8:9], v[2:5], off
	ds_read2_b32 v[8:9], v20 offset0:49 offset1:57
	ds_read2_b32 v[10:11], v20 offset0:16 offset1:24
	ds_read2_b32 v[12:13], v20 offset0:82 offset1:90
	ds_read2_b32 v[14:15], v20 offset0:115 offset1:123
	ds_read2_b32 v[16:17], v20 offset0:148 offset1:156
	ds_read2_b32 v[26:27], v20 offset0:181 offset1:189
	ds_read2_b32 v[28:29], v20 offset0:214 offset1:222
	ds_read2_b32 v[30:31], v20 offset0:247 offset1:255
	s_mov_b64 s[16:17], 0
	s_waitcnt lgkmcnt(6)
	v_cvt_pk_bf16_f32 v2, v10, v8
	v_or_b32_e32 v8, s2, v22
	v_or_b32_e32 v8, s18, v8
	v_lshlrev_b32_e32 v32, 11, v8
	v_or_b32_e32 v8, s2, v23
	s_waitcnt lgkmcnt(4)
	v_cvt_pk_bf16_f32 v3, v12, v14
	s_waitcnt lgkmcnt(2)
	v_cvt_pk_bf16_f32 v4, v16, v26
	s_waitcnt lgkmcnt(0)
	v_cvt_pk_bf16_f32 v5, v28, v30
	v_lshl_add_u64 v[32:33], v[6:7], 0, v[32:33]
	v_or_b32_e32 v8, s18, v8
	global_store_dwordx4 v[32:33], v[2:5], off
	v_lshlrev_b32_e32 v8, 11, v8
	s_mov_b64 s[18:19], -1
	v_cvt_pk_bf16_f32 v2, v11, v9
	v_mov_b32_e32 v9, v131
	v_cvt_pk_bf16_f32 v3, v13, v15
	v_cvt_pk_bf16_f32 v4, v17, v27
	v_cvt_pk_bf16_f32 v5, v29, v31
	v_lshl_add_u64 v[6:7], v[6:7], 0, v[8:9]
	global_store_dwordx4 v[6:7], v[2:5], off
	s_waitcnt lgkmcnt(0)

.LBB0_107:
	s_andn2_b64 vcc, exec, s[2:3]
	v_add_u32_e32 v12, 0x400, v18
	v_add_u32_e32 v11, 0x800, v18
	v_add_u32_e32 v10, 0xc00, v18
	v_add_u32_e32 v9, 0x1000, v18
	v_add_u32_e32 v8, 0x1400, v18
	v_add_u32_e32 v7, 0x1800, v18
	v_add_u32_e32 v6, 0x1c00, v18
	v_lshlrev_b32_e32 v2, 1, v0
	s_cbranch_vccnz .LBB0_109
	v_readlane_b32 s68, v249, 2
	s_lshl_b64 s[2:3], s[14:15], 2
	v_readlane_b32 s82, v249, 16
	v_readlane_b32 s83, v249, 17
	s_add_u32 s17, s82, s2
	s_mul_i32 s2, s20, 0xba2f
	s_addc_u32 s19, s83, s3
	s_lshr_b32 s3, s2, 16
	s_lshr_b32 s2, s2, 22
	s_mulk_i32 s2, 0x58
	s_sub_i32 s2, s20, s2
	s_and_b32 s16, s2, 0xffff
	s_and_b32 s3, s3, 0xffc0
	s_lshl_b32 s2, s16, 5
	s_lshl_b32 s18, s16, 7
	v_or_b32_e32 v3, s3, v128
	s_add_u32 s18, s17, s18
	s_addc_u32 s19, s19, 0
	v_mul_u32_u24_e32 v3, 0xb00, v3
	v_lshl_add_u64 v[4:5], s[18:19], 0, v[130:131]
	v_lshlrev_b32_e32 v14, 2, v3
	v_mov_b32_e32 v15, v131
	v_lshl_add_u64 v[4:5], v[4:5], 0, v[14:15]
	v_add_co_u32_e32 v14, vcc, s67, v4
	global_load_dword v3, v[4:5], off nt
	s_nop 0
	v_addc_co_u32_e32 v15, vcc, 0, v5, vcc
	global_load_dword v13, v[14:15], off offset:2048 nt
	v_add_co_u32_e32 v14, vcc, s6, v4
	s_lshl_b32 s16, s16, 6
	s_nop 0
	v_addc_co_u32_e32 v15, vcc, 0, v5, vcc
	global_load_dword v16, v[14:15], off nt
	v_add_co_u32_e32 v14, vcc, s46, v4
	s_and_b32 s18, s16, 0x1f00
	s_nop 0
	v_addc_co_u32_e32 v15, vcc, 0, v5, vcc
	global_load_dword v17, v[14:15], off offset:2048 nt
	v_add_co_u32_e32 v14, vcc, s48, v4
	s_lshl_b32 s3, s3, 1
	s_nop 0
	v_addc_co_u32_e32 v15, vcc, 0, v5, vcc
	global_load_dword v25, v[14:15], off nt
	v_add_co_u32_e32 v14, vcc, s34, v4
	s_add_u32 s16, s21, s3
	s_nop 0
	v_addc_co_u32_e32 v15, vcc, 0, v5, vcc
	global_load_dword v26, v[14:15], off offset:2048 nt
	v_add_co_u32_e32 v14, vcc, s7, v4
	s_addc_u32 s17, s22, 0
	s_nop 0
	v_addc_co_u32_e32 v15, vcc, 0, v5, vcc
	global_load_dword v27, v[14:15], off nt
	v_add_co_u32_e32 v14, vcc, s55, v4
	s_and_b32 s2, s2, 0x60
	s_nop 0
	v_addc_co_u32_e32 v15, vcc, 0, v5, vcc
	global_load_dword v28, v[14:15], off offset:2048 nt
	v_add_co_u32_e32 v14, vcc, s58, v4
	s_or_b32 s2, s18, s2
	s_nop 0
	v_addc_co_u32_e32 v15, vcc, 0, v5, vcc
	global_load_dword v29, v[14:15], off nt
	v_add_co_u32_e32 v14, vcc, s4, v4
	s_mov_b64 s[18:19], -1
	s_nop 0
	v_addc_co_u32_e32 v15, vcc, 0, v5, vcc
	global_load_dword v30, v[14:15], off offset:2048 nt
	v_add_co_u32_e32 v14, vcc, s5, v4
	s_mov_b32 s28, s20
	s_nop 0
	v_addc_co_u32_e32 v15, vcc, 0, v5, vcc
	global_load_dword v31, v[14:15], off nt
	v_add_co_u32_e32 v14, vcc, s65, v4
	v_readlane_b32 s69, v249, 3
	s_nop 0
	v_addc_co_u32_e32 v15, vcc, 0, v5, vcc
	global_load_dword v32, v[14:15], off offset:2048 nt
	v_add_co_u32_e32 v14, vcc, s39, v4
	v_readlane_b32 s70, v249, 4
	s_nop 0
	v_addc_co_u32_e32 v15, vcc, 0, v5, vcc
	global_load_dword v33, v[14:15], off nt
	v_add_co_u32_e32 v14, vcc, s41, v4
	v_readlane_b32 s71, v249, 5
	s_nop 0
	v_addc_co_u32_e32 v15, vcc, 0, v5, vcc
	global_load_dword v34, v[14:15], off offset:2048 nt
	v_add_co_u32_e32 v14, vcc, s42, v4
	v_readlane_b32 s72, v249, 6
	s_nop 0
	v_addc_co_u32_e32 v15, vcc, 0, v5, vcc
	global_load_dword v35, v[14:15], off nt
	v_add_co_u32_e32 v14, vcc, s43, v4
	v_readlane_b32 s73, v249, 7
	s_nop 0
	v_addc_co_u32_e32 v15, vcc, 0, v5, vcc
	global_load_dword v36, v[14:15], off offset:2048 nt
	v_add_co_u32_e32 v14, vcc, s44, v4
	v_readlane_b32 s74, v249, 8
	s_nop 0
	v_addc_co_u32_e32 v15, vcc, 0, v5, vcc
	global_load_dword v37, v[14:15], off nt
	v_add_co_u32_e32 v14, vcc, s45, v4
	v_readlane_b32 s75, v249, 9
	s_nop 0
	v_addc_co_u32_e32 v15, vcc, 0, v5, vcc
	global_load_dword v38, v[14:15], off offset:2048 nt
	v_add_co_u32_e32 v14, vcc, s47, v4
	v_readlane_b32 s76, v249, 10
	s_nop 0
	v_addc_co_u32_e32 v15, vcc, 0, v5, vcc
	global_load_dword v39, v[14:15], off nt
	v_add_co_u32_e32 v14, vcc, s49, v4
	v_readlane_b32 s77, v249, 11
	s_nop 0
	v_addc_co_u32_e32 v15, vcc, 0, v5, vcc
	global_load_dword v40, v[14:15], off offset:2048 nt
	v_add_co_u32_e32 v14, vcc, s50, v4
	v_readlane_b32 s78, v249, 12
	s_nop 0
	v_addc_co_u32_e32 v15, vcc, 0, v5, vcc
	global_load_dword v41, v[14:15], off nt
	v_add_co_u32_e32 v14, vcc, s51, v4
	v_readlane_b32 s79, v249, 13
	s_nop 0
	v_addc_co_u32_e32 v15, vcc, 0, v5, vcc
	global_load_dword v42, v[14:15], off offset:2048 nt
	v_add_co_u32_e32 v14, vcc, s52, v4
	v_readlane_b32 s80, v249, 14
	s_nop 0
	v_addc_co_u32_e32 v15, vcc, 0, v5, vcc
	global_load_dword v43, v[14:15], off nt
	v_add_co_u32_e32 v14, vcc, s53, v4
	v_readlane_b32 s81, v249, 15
	s_nop 0
	v_addc_co_u32_e32 v15, vcc, 0, v5, vcc
	global_load_dword v44, v[14:15], off offset:2048 nt
	v_add_co_u32_e32 v14, vcc, s84, v4
	s_nop 1
	v_addc_co_u32_e32 v15, vcc, 0, v5, vcc
	global_load_dword v45, v[14:15], off nt
	v_add_co_u32_e32 v14, vcc, s85, v4
	s_nop 1
	v_addc_co_u32_e32 v15, vcc, 0, v5, vcc
	global_load_dword v46, v[14:15], off offset:2048 nt
	v_add_co_u32_e32 v14, vcc, s86, v4
	s_nop 1
	v_addc_co_u32_e32 v15, vcc, 0, v5, vcc
	global_load_dword v47, v[14:15], off nt
	v_add_co_u32_e32 v14, vcc, s87, v4
	s_nop 1
	v_addc_co_u32_e32 v15, vcc, 0, v5, vcc
	global_load_dword v48, v[14:15], off offset:2048 nt
	v_add_co_u32_e32 v14, vcc, s88, v4
	s_nop 1
	v_addc_co_u32_e32 v15, vcc, 0, v5, vcc
	global_load_dword v49, v[14:15], off nt
	v_add_co_u32_e32 v14, vcc, s89, v4
	s_nop 1
	v_addc_co_u32_e32 v15, vcc, 0, v5, vcc
	global_load_dword v50, v[14:15], off offset:2048 nt
	v_add_co_u32_e32 v14, vcc, s90, v4
	s_nop 1
	v_addc_co_u32_e32 v15, vcc, 0, v5, vcc
	v_add_co_u32_e32 v4, vcc, s91, v4
	global_load_dword v14, v[14:15], off nt
	s_nop 0
	v_addc_co_u32_e32 v5, vcc, 0, v5, vcc
	global_load_dword v4, v[4:5], off offset:2048 nt
	s_waitcnt vmcnt(30)
	ds_write2_b32 v18, v3, v13 offset1:66
	s_waitcnt vmcnt(28)
	ds_write2_b32 v18, v16, v17 offset0:132 offset1:198
	s_waitcnt vmcnt(26)
	ds_write2_b32 v12, v25, v26 offset0:8 offset1:74
	s_waitcnt vmcnt(24)
	ds_write2_b32 v12, v27, v28 offset0:140 offset1:206
	s_waitcnt vmcnt(22)
	ds_write2_b32 v11, v29, v30 offset0:16 offset1:82
	s_waitcnt vmcnt(20)
	ds_write2_b32 v11, v31, v32 offset0:148 offset1:214
	s_waitcnt vmcnt(18)
	ds_write2_b32 v10, v33, v34 offset0:24 offset1:90
	s_waitcnt vmcnt(16)
	ds_write2_b32 v10, v35, v36 offset0:156 offset1:222
	s_waitcnt vmcnt(14)
	ds_write2_b32 v9, v37, v38 offset0:32 offset1:98
	s_waitcnt vmcnt(12)
	ds_write2_b32 v9, v39, v40 offset0:164 offset1:230
	s_waitcnt vmcnt(10)
	ds_write2_b32 v8, v41, v42 offset0:40 offset1:106
	s_waitcnt vmcnt(8)
	ds_write2_b32 v8, v43, v44 offset0:172 offset1:238
	s_waitcnt vmcnt(6)
	ds_write2_b32 v7, v45, v46 offset0:48 offset1:114
	s_waitcnt vmcnt(4)
	ds_write2_b32 v7, v47, v48 offset0:180 offset1:246
	s_waitcnt vmcnt(2)
	ds_write2_b32 v6, v49, v50 offset0:56 offset1:122
	s_waitcnt vmcnt(0)
	ds_write2_b32 v6, v14, v4 offset0:188 offset1:254
	s_waitcnt lgkmcnt(0)
	ds_read2_b32 v[26:27], v20 offset0:33 offset1:41
	ds_read2_b32 v[28:29], v20 offset1:8
	ds_read2_b32 v[30:31], v20 offset0:66 offset1:74
	ds_read2_b32 v[32:33], v20 offset0:99 offset1:107
	ds_read2_b32 v[34:35], v20 offset0:132 offset1:140
	ds_read2_b32 v[36:37], v20 offset0:165 offset1:173
	ds_read2_b32 v[38:39], v20 offset0:198 offset1:206
	ds_read2_b32 v[40:41], v20 offset0:231 offset1:239
	v_mov_b32_e32 v3, v131
	v_lshl_add_u64 v[4:5], s[16:17], 0, v[2:3]
	v_or_b32_e32 v3, s2, v19
	v_lshlrev_b32_e32 v42, 11, v3
	v_mov_b32_e32 v43, v131
	s_waitcnt lgkmcnt(6)
	v_cvt_pk_bf16_f32 v14, v28, v26
	s_waitcnt lgkmcnt(4)
	v_cvt_pk_bf16_f32 v15, v30, v32
	s_waitcnt lgkmcnt(2)
	v_cvt_pk_bf16_f32 v16, v34, v36
	s_waitcnt lgkmcnt(0)
	v_cvt_pk_bf16_f32 v17, v38, v40
	v_lshl_add_u64 v[42:43], v[4:5], 0, v[42:43]
	v_or_b32_e32 v3, s2, v21
	global_store_dwordx4 v[42:43], v[14:17], off
	v_lshlrev_b32_e32 v26, 11, v3
	v_or_b32_e32 v3, s2, v22
	v_cvt_pk_bf16_f32 v14, v29, v27
	v_mov_b32_e32 v27, v131
	v_cvt_pk_bf16_f32 v15, v31, v33
	v_cvt_pk_bf16_f32 v16, v35, v37
	v_cvt_pk_bf16_f32 v17, v39, v41
	v_lshl_add_u64 v[26:27], v[4:5], 0, v[26:27]
	global_store_dwordx4 v[26:27], v[14:17], off
	ds_read2_b32 v[26:27], v20 offset0:49 offset1:57
	ds_read2_b32 v[28:29], v20 offset0:16 offset1:24
	ds_read2_b32 v[30:31], v20 offset0:82 offset1:90
	ds_read2_b32 v[32:33], v20 offset0:115 offset1:123
	ds_read2_b32 v[34:35], v20 offset0:148 offset1:156
	ds_read2_b32 v[36:37], v20 offset0:181 offset1:189
	ds_read2_b32 v[38:39], v20 offset0:214 offset1:222
	ds_read2_b32 v[40:41], v20 offset0:247 offset1:255
	v_lshlrev_b32_e32 v42, 11, v3
	v_mov_b32_e32 v43, v131
	s_waitcnt lgkmcnt(6)
	v_cvt_pk_bf16_f32 v14, v28, v26
	s_waitcnt lgkmcnt(4)
	v_cvt_pk_bf16_f32 v15, v30, v32
	s_waitcnt lgkmcnt(2)
	v_cvt_pk_bf16_f32 v16, v34, v36
	s_waitcnt lgkmcnt(0)
	v_cvt_pk_bf16_f32 v17, v38, v40
	v_lshl_add_u64 v[42:43], v[4:5], 0, v[42:43]
	v_or_b32_e32 v3, s2, v23
	global_store_dwordx4 v[42:43], v[14:17], off
	v_lshlrev_b32_e32 v26, 11, v3
	s_mov_b64 s[16:17], 0
	v_cvt_pk_bf16_f32 v14, v29, v27
	v_mov_b32_e32 v27, v131
	v_cvt_pk_bf16_f32 v15, v31, v33
	v_cvt_pk_bf16_f32 v16, v35, v37
	v_cvt_pk_bf16_f32 v17, v39, v41
	v_lshl_add_u64 v[4:5], v[4:5], 0, v[26:27]
	global_store_dwordx4 v[4:5], v[14:17], off
	s_waitcnt lgkmcnt(0)

.LBB0_117:
	s_andn2_b64 vcc, exec, s[20:21]
	s_cbranch_vccnz .LBB0_124
	s_cmpk_gt_u32 s24, 0x47f
	s_mov_b64 s[20:21], -1
	s_cbranch_scc0 .LBB0_120
	v_readlane_b32 s68, v249, 18
	s_lshl_b64 s[20:21], s[8:9], 22
	v_readlane_b32 s76, v249, 26
	v_readlane_b32 s77, v249, 27
	s_add_u32 s25, s76, s20
	s_addc_u32 vcc_hi, s77, s21
	s_lshl_b64 s[22:23], s[8:9], 21
	v_readlane_b32 s20, v250, 0
	s_add_u32 s21, s20, s22
	v_readlane_b32 s20, v250, 1
	s_addc_u32 s22, s20, s23
	s_lshl_b32 s20, s24, 1
	s_add_i32 s20, s20, 0x1f700
	s_and_b32 s23, s20, 0x1ffc0
	s_lshl_b32 s20, s24, 5
	s_and_b32 s20, s20, 0x3e0
	s_lshl_b32 vcc_lo, s20, 2
	s_add_u32 vcc_lo, s25, vcc_lo
	v_or_b32_e32 v3, s23, v128
	s_addc_u32 vcc_hi, vcc_hi, 0
	v_lshl_add_u64 v[4:5], vcc, 0, v[130:131]
	v_lshlrev_b32_e32 v14, 12, v3
	v_mov_b32_e32 v15, v131
	v_lshl_add_u64 v[4:5], v[4:5], 0, v[14:15]
	s_movk_i32 s25, 0x2000
	v_add_co_u32_e32 v14, vcc, s25, v4
	global_load_dword v3, v[4:5], off nt
	s_nop 0
	v_addc_co_u32_e32 v15, vcc, 0, v5, vcc
	global_load_dword v13, v[14:15], off nt
	v_add_co_u32_e32 v14, vcc, s40, v4
	s_movk_i32 s25, 0x6000
	s_nop 0
	v_addc_co_u32_e32 v15, vcc, 0, v5, vcc
	global_load_dword v16, v[14:15], off nt
	v_add_co_u32_e32 v14, vcc, s25, v4
	s_mov_b32 s25, 0x8000
	s_nop 0
	v_addc_co_u32_e32 v15, vcc, 0, v5, vcc
	global_load_dword v17, v[14:15], off nt
	v_add_co_u32_e32 v14, vcc, s25, v4
	s_mov_b32 s25, 0xa000
	s_nop 0
	v_addc_co_u32_e32 v15, vcc, 0, v5, vcc
	global_load_dword v25, v[14:15], off nt
	v_add_co_u32_e32 v14, vcc, s25, v4
	s_mov_b32 s25, 0xc000
	s_nop 0
	v_addc_co_u32_e32 v15, vcc, 0, v5, vcc
	global_load_dword v26, v[14:15], off nt
	v_add_co_u32_e32 v14, vcc, s25, v4
	s_mov_b32 s25, 0xe000
	s_nop 0
	v_addc_co_u32_e32 v15, vcc, 0, v5, vcc
	global_load_dword v27, v[14:15], off nt
	v_add_co_u32_e32 v14, vcc, s25, v4
	s_mov_b32 s25, 0x14000
	s_nop 0
	v_addc_co_u32_e32 v15, vcc, 0, v5, vcc
	global_load_dword v28, v[14:15], off nt
	v_add_co_u32_e32 v14, vcc, s46, v4
	s_lshl_b32 s23, s23, 1
	s_nop 0
	v_addc_co_u32_e32 v15, vcc, 0, v5, vcc
	global_load_dword v29, v[14:15], off nt
	v_add_co_u32_e32 v14, vcc, s31, v4
	v_readlane_b32 s69, v249, 19
	s_nop 0
	v_addc_co_u32_e32 v15, vcc, 0, v5, vcc
	global_load_dword v30, v[14:15], off nt
	v_add_co_u32_e32 v14, vcc, s25, v4
	s_mov_b32 s25, 0x18000
	s_nop 0
	v_addc_co_u32_e32 v15, vcc, 0, v5, vcc
	global_load_dword v31, v[14:15], off nt
	v_add_co_u32_e32 v14, vcc, s48, v4
	v_readlane_b32 s70, v249, 20
	s_nop 0
	v_addc_co_u32_e32 v15, vcc, 0, v5, vcc
	global_load_dword v32, v[14:15], off nt
	v_add_co_u32_e32 v14, vcc, s25, v4
	s_mov_b32 s25, 0x1a000
	s_nop 0
	v_addc_co_u32_e32 v15, vcc, 0, v5, vcc
	global_load_dword v33, v[14:15], off nt
	v_add_co_u32_e32 v14, vcc, s25, v4
	s_mov_b32 s25, 0x1c000
	s_nop 0
	v_addc_co_u32_e32 v15, vcc, 0, v5, vcc
	global_load_dword v34, v[14:15], off nt
	v_add_co_u32_e32 v14, vcc, s25, v4
	s_mov_b32 s25, 0x1e000
	s_nop 0
	v_addc_co_u32_e32 v15, vcc, 0, v5, vcc
	global_load_dword v35, v[14:15], off nt
	v_add_co_u32_e32 v14, vcc, s25, v4
	s_mov_b32 s25, 0x20000
	s_nop 0
	v_addc_co_u32_e32 v15, vcc, 0, v5, vcc
	global_load_dword v36, v[14:15], off nt
	v_add_co_u32_e32 v14, vcc, s25, v4
	v_readlane_b32 s71, v249, 21
	s_nop 0
	v_addc_co_u32_e32 v15, vcc, 0, v5, vcc
	global_load_dword v37, v[14:15], off nt
	v_add_co_u32_e32 v14, vcc, s54, v4
	v_readlane_b32 s72, v249, 22
	s_nop 0
	v_addc_co_u32_e32 v15, vcc, 0, v5, vcc
	global_load_dword v38, v[14:15], off nt
	v_add_co_u32_e32 v14, vcc, s35, v4
	v_readlane_b32 s73, v249, 23
	s_nop 0
	v_addc_co_u32_e32 v15, vcc, 0, v5, vcc
	global_load_dword v39, v[14:15], off nt
	v_add_co_u32_e32 v14, vcc, s55, v4
	v_readlane_b32 s74, v249, 24
	s_nop 0
	v_addc_co_u32_e32 v15, vcc, 0, v5, vcc
	global_load_dword v40, v[14:15], off nt
	v_add_co_u32_e32 v14, vcc, s56, v4
	v_readlane_b32 s75, v249, 25
	s_nop 0
	v_addc_co_u32_e32 v15, vcc, 0, v5, vcc
	global_load_dword v41, v[14:15], off nt
	v_add_co_u32_e32 v14, vcc, s57, v4
	v_readlane_b32 s78, v249, 28
	s_nop 0
	v_addc_co_u32_e32 v15, vcc, 0, v5, vcc
	global_load_dword v42, v[14:15], off nt
	v_add_co_u32_e32 v14, vcc, s58, v4
	v_readlane_b32 s79, v249, 29
	s_nop 0
	v_addc_co_u32_e32 v15, vcc, 0, v5, vcc
	global_load_dword v43, v[14:15], off nt
	v_add_co_u32_e32 v14, vcc, s59, v4
	v_readlane_b32 s80, v249, 30
	s_nop 0
	v_addc_co_u32_e32 v15, vcc, 0, v5, vcc
	global_load_dword v44, v[14:15], off nt
	v_add_co_u32_e32 v14, vcc, s60, v4
	v_readlane_b32 s81, v249, 31
	s_nop 0
	v_addc_co_u32_e32 v15, vcc, 0, v5, vcc
	global_load_dword v45, v[14:15], off nt
	v_add_co_u32_e32 v14, vcc, s61, v4
	v_readlane_b32 s82, v249, 32
	s_nop 0
	v_addc_co_u32_e32 v15, vcc, 0, v5, vcc
	global_load_dword v46, v[14:15], off nt
	v_add_co_u32_e32 v14, vcc, s62, v4
	v_readlane_b32 s83, v249, 33
	s_nop 0
	v_addc_co_u32_e32 v15, vcc, 0, v5, vcc
	global_load_dword v47, v[14:15], off nt
	v_add_co_u32_e32 v14, vcc, s37, v4
	s_nop 1
	v_addc_co_u32_e32 v15, vcc, 0, v5, vcc
	global_load_dword v48, v[14:15], off nt
	v_add_co_u32_e32 v14, vcc, s63, v4
	s_nop 1
	v_addc_co_u32_e32 v15, vcc, 0, v5, vcc
	global_load_dword v49, v[14:15], off nt
	v_add_co_u32_e32 v14, vcc, s64, v4
	s_nop 1
	v_addc_co_u32_e32 v15, vcc, 0, v5, vcc
	global_load_dword v50, v[14:15], off nt
	v_add_co_u32_e32 v14, vcc, s65, v4
	s_nop 1
	v_addc_co_u32_e32 v15, vcc, 0, v5, vcc
	v_add_co_u32_e32 v4, vcc, s66, v4
	global_load_dword v14, v[14:15], off nt
	s_nop 0
	v_addc_co_u32_e32 v5, vcc, 0, v5, vcc
	global_load_dword v4, v[4:5], off nt
	s_waitcnt vmcnt(30)
	ds_write2_b32 v18, v3, v13 offset1:66
	s_waitcnt vmcnt(28)
	ds_write2_b32 v18, v16, v17 offset0:132 offset1:198
	s_waitcnt vmcnt(26)
	ds_write2_b32 v12, v25, v26 offset0:8 offset1:74
	s_waitcnt vmcnt(24)
	ds_write2_b32 v12, v27, v28 offset0:140 offset1:206
	s_waitcnt vmcnt(22)
	ds_write2_b32 v11, v29, v30 offset0:16 offset1:82
	s_waitcnt vmcnt(20)
	ds_write2_b32 v11, v31, v32 offset0:148 offset1:214
	s_waitcnt vmcnt(18)
	ds_write2_b32 v10, v33, v34 offset0:24 offset1:90
	s_waitcnt vmcnt(16)
	ds_write2_b32 v10, v35, v36 offset0:156 offset1:222
	s_waitcnt vmcnt(14)
	ds_write2_b32 v9, v37, v38 offset0:32 offset1:98
	s_waitcnt vmcnt(12)
	ds_write2_b32 v9, v39, v40 offset0:164 offset1:230
	s_waitcnt vmcnt(10)
	ds_write2_b32 v8, v41, v42 offset0:40 offset1:106
	s_waitcnt vmcnt(8)
	ds_write2_b32 v8, v43, v44 offset0:172 offset1:238
	s_waitcnt vmcnt(6)
	ds_write2_b32 v7, v45, v46 offset0:48 offset1:114
	s_waitcnt vmcnt(4)
	ds_write2_b32 v7, v47, v48 offset0:180 offset1:246
	s_waitcnt vmcnt(2)
	ds_write2_b32 v6, v49, v50 offset0:56 offset1:122
	s_waitcnt vmcnt(0)
	ds_write2_b32 v6, v14, v4 offset0:188 offset1:254
	s_waitcnt lgkmcnt(0)
	ds_read2_b32 v[26:27], v20 offset0:33 offset1:41
	ds_read2_b32 v[28:29], v20 offset1:8
	ds_read2_b32 v[30:31], v20 offset0:66 offset1:74
	ds_read2_b32 v[32:33], v20 offset0:99 offset1:107
	ds_read2_b32 v[34:35], v20 offset0:132 offset1:140
	ds_read2_b32 v[36:37], v20 offset0:165 offset1:173
	ds_read2_b32 v[38:39], v20 offset0:198 offset1:206
	ds_read2_b32 v[40:41], v20 offset0:231 offset1:239
	s_add_u32 vcc_lo, s21, s23
	s_addc_u32 vcc_hi, s22, 0
	v_mov_b32_e32 v3, v131
	v_lshl_add_u64 v[4:5], vcc, 0, v[2:3]
	v_or_b32_e32 v3, s20, v19
	v_lshlrev_b32_e32 v42, 11, v3
	v_mov_b32_e32 v43, v131
	s_waitcnt lgkmcnt(6)
	v_cvt_pk_bf16_f32 v14, v28, v26
	s_waitcnt lgkmcnt(4)
	v_cvt_pk_bf16_f32 v15, v30, v32
	s_waitcnt lgkmcnt(2)
	v_cvt_pk_bf16_f32 v16, v34, v36
	s_waitcnt lgkmcnt(0)
	v_cvt_pk_bf16_f32 v17, v38, v40
	v_lshl_add_u64 v[42:43], v[4:5], 0, v[42:43]
	v_or_b32_e32 v3, s20, v21
	global_store_dwordx4 v[42:43], v[14:17], off
	v_lshlrev_b32_e32 v26, 11, v3
	v_or_b32_e32 v3, s20, v22
	v_cvt_pk_bf16_f32 v14, v29, v27
	v_mov_b32_e32 v27, v131
	v_cvt_pk_bf16_f32 v15, v31, v33
	v_cvt_pk_bf16_f32 v16, v35, v37
	v_cvt_pk_bf16_f32 v17, v39, v41
	v_lshl_add_u64 v[26:27], v[4:5], 0, v[26:27]
	global_store_dwordx4 v[26:27], v[14:17], off
	ds_read2_b32 v[26:27], v20 offset0:49 offset1:57
	ds_read2_b32 v[28:29], v20 offset0:16 offset1:24
	ds_read2_b32 v[30:31], v20 offset0:82 offset1:90
	ds_read2_b32 v[32:33], v20 offset0:115 offset1:123
	ds_read2_b32 v[34:35], v20 offset0:148 offset1:156
	ds_read2_b32 v[36:37], v20 offset0:181 offset1:189
	ds_read2_b32 v[38:39], v20 offset0:214 offset1:222
	ds_read2_b32 v[40:41], v20 offset0:247 offset1:255
	v_lshlrev_b32_e32 v42, 11, v3
	v_mov_b32_e32 v43, v131
	s_waitcnt lgkmcnt(6)
	v_cvt_pk_bf16_f32 v14, v28, v26
	s_waitcnt lgkmcnt(4)
	v_cvt_pk_bf16_f32 v15, v30, v32
	s_waitcnt lgkmcnt(2)
	v_cvt_pk_bf16_f32 v16, v34, v36
	s_waitcnt lgkmcnt(0)
	v_cvt_pk_bf16_f32 v17, v38, v40
	v_lshl_add_u64 v[42:43], v[4:5], 0, v[42:43]
	v_or_b32_e32 v3, s20, v23
	global_store_dwordx4 v[42:43], v[14:17], off
	v_lshlrev_b32_e32 v26, 11, v3
	s_mov_b64 s[20:21], 0
	v_cvt_pk_bf16_f32 v14, v29, v27
	v_mov_b32_e32 v27, v131
	v_cvt_pk_bf16_f32 v15, v31, v33
	v_cvt_pk_bf16_f32 v16, v35, v37
	v_cvt_pk_bf16_f32 v17, v39, v41
	v_lshl_add_u64 v[4:5], v[4:5], 0, v[26:27]
	global_store_dwordx4 v[4:5], v[14:17], off
	s_waitcnt lgkmcnt(0)
.LBB0_120:
	s_andn2_b64 vcc, exec, s[20:21]
	s_cbranch_vccnz .LBB0_124
	v_readlane_b32 s68, v249, 18
	s_mul_i32 s21, s8, 0x900000
	v_readlane_b32 s74, v249, 24
	s_mul_hi_u32 s20, s8, 0x900000
	v_readlane_b32 s75, v249, 25
	s_add_u32 s23, s74, s21
	s_addc_u32 s25, s75, s20
	s_mul_hi_u32 s21, s8, 0x480000
	s_mul_i32 s8, s8, 0x480000
	v_readlane_b32 s20, v250, 2
	s_add_u32 s20, s20, s8
	v_readlane_b32 s8, v250, 3
	s_addc_u32 s21, s8, s21
	s_and_b32 s8, s24, 0xffff
	s_mul_i32 s8, s8, 0xe38f
	s_lshr_b32 s22, s8, 16
	s_lshr_b32 s8, s8, 22
	s_mulk_i32 s8, 0x48
	s_sub_i32 s8, s24, s8
	s_lshl_b32 s8, s8, 5
	s_and_b32 s8, s8, 0xffe0
	s_and_b32 s22, s22, 0xffc0
	s_lshl_b32 s24, s8, 2
	v_or_b32_e32 v3, s22, v128
	s_add_u32 s24, s23, s24
	s_addc_u32 s25, s25, 0
	v_mul_u32_u24_e32 v3, 0x900, v3
	v_lshl_add_u64 v[4:5], s[24:25], 0, v[130:131]
	v_lshlrev_b32_e32 v14, 2, v3
	v_mov_b32_e32 v15, v131
	v_lshl_add_u64 v[4:5], v[4:5], 0, v[14:15]
	v_add_co_u32_e32 v14, vcc, s40, v4
	s_mov_b32 s23, 0xd000
	s_nop 0
	v_addc_co_u32_e32 v15, vcc, 0, v5, vcc
	global_load_dword v13, v[14:15], off offset:2048 nt
	v_add_co_u32_e32 v14, vcc, s33, v4
	global_load_dword v3, v[4:5], off nt
	s_nop 0
	v_addc_co_u32_e32 v15, vcc, 0, v5, vcc
	global_load_dword v16, v[14:15], off nt
	v_add_co_u32_e32 v14, vcc, s23, v4
	s_mov_b32 s23, 0x1f000
	s_nop 0
	v_addc_co_u32_e32 v15, vcc, 0, v5, vcc
	global_load_dword v17, v[14:15], off offset:2048 nt
	v_add_co_u32_e32 v14, vcc, s31, v4
	s_lshl_b32 s22, s22, 1
	s_nop 0
	v_addc_co_u32_e32 v15, vcc, 0, v5, vcc
	global_load_dword v25, v[14:15], off nt
	v_add_co_u32_e32 v14, vcc, s48, v4
	s_add_u32 s20, s20, s22
	s_nop 0
	v_addc_co_u32_e32 v15, vcc, 0, v5, vcc
	global_load_dword v26, v[14:15], off offset:2048 nt
	v_add_co_u32_e32 v14, vcc, s34, v4
	s_addc_u32 s21, s21, 0
	s_nop 0
	v_addc_co_u32_e32 v15, vcc, 0, v5, vcc
	global_load_dword v27, v[14:15], off nt
	v_add_co_u32_e32 v14, vcc, s23, v4
	s_mov_b32 s23, 0x43000
	s_nop 0
	v_addc_co_u32_e32 v15, vcc, 0, v5, vcc
	global_load_dword v28, v[14:15], off offset:2048 nt
	v_add_co_u32_e32 v14, vcc, s35, v4
	v_readlane_b32 s69, v249, 19
	s_nop 0
	v_addc_co_u32_e32 v15, vcc, 0, v5, vcc
	global_load_dword v29, v[14:15], off nt
	v_add_co_u32_e32 v14, vcc, s56, v4
	v_readlane_b32 s70, v249, 20
	s_nop 0
	v_addc_co_u32_e32 v15, vcc, 0, v5, vcc
	global_load_dword v30, v[14:15], off offset:2048 nt
	v_add_co_u32_e32 v14, vcc, s36, v4
	v_readlane_b32 s71, v249, 21
	s_nop 0
	v_addc_co_u32_e32 v15, vcc, 0, v5, vcc
	global_load_dword v31, v[14:15], off nt
	v_add_co_u32_e32 v14, vcc, s4, v4
	v_readlane_b32 s72, v249, 22
	s_nop 0
	v_addc_co_u32_e32 v15, vcc, 0, v5, vcc
	global_load_dword v32, v[14:15], off offset:2048 nt
	v_add_co_u32_e32 v14, vcc, s37, v4
	v_readlane_b32 s73, v249, 23
	s_nop 0
	v_addc_co_u32_e32 v15, vcc, 0, v5, vcc
	global_load_dword v33, v[14:15], off nt
	v_add_co_u32_e32 v14, vcc, s64, v4
	v_readlane_b32 s76, v249, 26
	s_nop 0
	v_addc_co_u32_e32 v15, vcc, 0, v5, vcc
	global_load_dword v34, v[14:15], off offset:2048 nt
	v_add_co_u32_e32 v14, vcc, s38, v4
	v_readlane_b32 s77, v249, 27
	s_nop 0
	v_addc_co_u32_e32 v15, vcc, 0, v5, vcc
	global_load_dword v35, v[14:15], off nt
	v_add_co_u32_e32 v14, vcc, s23, v4
	s_mov_b32 s23, 0x48000
	s_nop 0
	v_addc_co_u32_e32 v15, vcc, 0, v5, vcc
	global_load_dword v36, v[14:15], off offset:2048 nt
	v_add_co_u32_e32 v14, vcc, s23, v4
	s_mov_b32 s23, 0x4c000
	s_nop 0
	v_addc_co_u32_e32 v15, vcc, 0, v5, vcc
	global_load_dword v37, v[14:15], off nt
	v_add_co_u32_e32 v14, vcc, s23, v4
	s_mov_b32 s23, 0x51000
	s_nop 0
	v_addc_co_u32_e32 v15, vcc, 0, v5, vcc
	global_load_dword v38, v[14:15], off offset:2048 nt
	v_add_co_u32_e32 v14, vcc, s23, v4
	s_mov_b32 s23, 0x55000
	s_nop 0
	v_addc_co_u32_e32 v15, vcc, 0, v5, vcc
	global_load_dword v39, v[14:15], off nt
	v_add_co_u32_e32 v14, vcc, s23, v4
	s_mov_b32 s23, 0x5a000
	s_nop 0
	v_addc_co_u32_e32 v15, vcc, 0, v5, vcc
	global_load_dword v40, v[14:15], off offset:2048 nt
	v_add_co_u32_e32 v14, vcc, s23, v4
	s_mov_b32 s23, 0x5e000
	s_nop 0
	v_addc_co_u32_e32 v15, vcc, 0, v5, vcc
	global_load_dword v41, v[14:15], off nt
	v_add_co_u32_e32 v14, vcc, s23, v4
	s_mov_b32 s23, 0x67000
	s_nop 0
	v_addc_co_u32_e32 v15, vcc, 0, v5, vcc
	global_load_dword v42, v[14:15], off offset:2048 nt
	v_add_co_u32_e32 v14, vcc, s47, v4
	v_readlane_b32 s78, v249, 28
	s_nop 0
	v_addc_co_u32_e32 v15, vcc, 0, v5, vcc
	global_load_dword v43, v[14:15], off nt
	v_add_co_u32_e32 v14, vcc, s23, v4
	s_mov_b32 s23, 0x6c000
	s_nop 0
	v_addc_co_u32_e32 v15, vcc, 0, v5, vcc
	global_load_dword v44, v[14:15], off offset:2048 nt
	v_add_co_u32_e32 v14, vcc, s23, v4
	s_mov_b32 s23, 0x70000
	s_nop 0
	v_addc_co_u32_e32 v15, vcc, 0, v5, vcc
	global_load_dword v45, v[14:15], off nt
	v_add_co_u32_e32 v14, vcc, s23, v4
	s_mov_b32 s23, 0x75000
	s_nop 0
	v_addc_co_u32_e32 v15, vcc, 0, v5, vcc
	global_load_dword v46, v[14:15], off offset:2048 nt
	v_add_co_u32_e32 v14, vcc, s23, v4
	s_mov_b32 s23, 0x82000
	s_nop 0
	v_addc_co_u32_e32 v15, vcc, 0, v5, vcc
	global_load_dword v47, v[14:15], off nt
	v_add_co_u32_e32 v14, vcc, s52, v4
	v_readlane_b32 s79, v249, 29
	s_nop 0
	v_addc_co_u32_e32 v15, vcc, 0, v5, vcc
	global_load_dword v48, v[14:15], off offset:2048 nt
	v_add_co_u32_e32 v14, vcc, s53, v4
	v_readlane_b32 s80, v249, 30
	s_nop 0
	v_addc_co_u32_e32 v15, vcc, 0, v5, vcc
	global_load_dword v49, v[14:15], off nt
	v_add_co_u32_e32 v14, vcc, s23, v4
	s_mov_b32 s23, 0x87000
	s_nop 0
	v_addc_co_u32_e32 v15, vcc, 0, v5, vcc
	global_load_dword v50, v[14:15], off offset:2048 nt
	v_add_co_u32_e32 v14, vcc, s23, v4
	s_mov_b32 s23, 0x8b000
	s_nop 0
	v_addc_co_u32_e32 v15, vcc, 0, v5, vcc
	v_add_co_u32_e32 v4, vcc, s23, v4
	global_load_dword v14, v[14:15], off nt
	s_nop 0
	v_addc_co_u32_e32 v5, vcc, 0, v5, vcc
	global_load_dword v4, v[4:5], off offset:2048 nt
	s_waitcnt vmcnt(30)
	ds_write2_b32 v18, v3, v13 offset1:66
	s_waitcnt vmcnt(28)
	ds_write2_b32 v18, v16, v17 offset0:132 offset1:198
	s_waitcnt vmcnt(26)
	ds_write2_b32 v12, v25, v26 offset0:8 offset1:74
	s_waitcnt vmcnt(24)
	ds_write2_b32 v12, v27, v28 offset0:140 offset1:206
	s_waitcnt vmcnt(22)
	ds_write2_b32 v11, v29, v30 offset0:16 offset1:82
	s_waitcnt vmcnt(20)
	ds_write2_b32 v11, v31, v32 offset0:148 offset1:214
	s_waitcnt vmcnt(18)
	ds_write2_b32 v10, v33, v34 offset0:24 offset1:90
	s_waitcnt vmcnt(16)
	ds_write2_b32 v10, v35, v36 offset0:156 offset1:222
	s_waitcnt vmcnt(14)
	ds_write2_b32 v9, v37, v38 offset0:32 offset1:98
	s_waitcnt vmcnt(12)
	ds_write2_b32 v9, v39, v40 offset0:164 offset1:230
	s_waitcnt vmcnt(10)
	ds_write2_b32 v8, v41, v42 offset0:40 offset1:106
	s_waitcnt vmcnt(8)
	ds_write2_b32 v8, v43, v44 offset0:172 offset1:238
	s_waitcnt vmcnt(6)
	ds_write2_b32 v7, v45, v46 offset0:48 offset1:114
	s_waitcnt vmcnt(4)
	ds_write2_b32 v7, v47, v48 offset0:180 offset1:246
	s_waitcnt vmcnt(2)
	ds_write2_b32 v6, v49, v50 offset0:56 offset1:122
	s_waitcnt vmcnt(0)
	ds_write2_b32 v6, v14, v4 offset0:188 offset1:254
	s_waitcnt lgkmcnt(0)
	ds_read2_b32 v[26:27], v20 offset0:33 offset1:41
	ds_read2_b32 v[28:29], v20 offset1:8
	ds_read2_b32 v[30:31], v20 offset0:66 offset1:74
	ds_read2_b32 v[32:33], v20 offset0:99 offset1:107
	ds_read2_b32 v[34:35], v20 offset0:132 offset1:140
	ds_read2_b32 v[36:37], v20 offset0:165 offset1:173
	ds_read2_b32 v[38:39], v20 offset0:198 offset1:206
	ds_read2_b32 v[40:41], v20 offset0:231 offset1:239
	v_mov_b32_e32 v3, v131
	v_lshl_add_u64 v[4:5], s[20:21], 0, v[2:3]
	v_or_b32_e32 v3, s8, v19
	v_lshlrev_b32_e32 v42, 11, v3
	v_mov_b32_e32 v43, v131
	s_waitcnt lgkmcnt(6)
	v_cvt_pk_bf16_f32 v14, v28, v26
	s_waitcnt lgkmcnt(4)
	v_cvt_pk_bf16_f32 v15, v30, v32
	s_waitcnt lgkmcnt(2)
	v_cvt_pk_bf16_f32 v16, v34, v36
	s_waitcnt lgkmcnt(0)
	v_cvt_pk_bf16_f32 v17, v38, v40
	v_lshl_add_u64 v[42:43], v[4:5], 0, v[42:43]
	v_or_b32_e32 v3, s8, v21
	global_store_dwordx4 v[42:43], v[14:17], off
	v_lshlrev_b32_e32 v26, 11, v3
	v_or_b32_e32 v3, s8, v22
	v_cvt_pk_bf16_f32 v14, v29, v27
	v_mov_b32_e32 v27, v131
	v_cvt_pk_bf16_f32 v15, v31, v33
	v_cvt_pk_bf16_f32 v16, v35, v37
	v_cvt_pk_bf16_f32 v17, v39, v41
	v_lshl_add_u64 v[26:27], v[4:5], 0, v[26:27]
	global_store_dwordx4 v[26:27], v[14:17], off
	ds_read2_b32 v[26:27], v20 offset0:49 offset1:57
	ds_read2_b32 v[28:29], v20 offset0:16 offset1:24
	ds_read2_b32 v[30:31], v20 offset0:82 offset1:90
	ds_read2_b32 v[32:33], v20 offset0:115 offset1:123
	ds_read2_b32 v[34:35], v20 offset0:148 offset1:156
	ds_read2_b32 v[36:37], v20 offset0:181 offset1:189
	ds_read2_b32 v[38:39], v20 offset0:214 offset1:222
	ds_read2_b32 v[40:41], v20 offset0:247 offset1:255
	v_lshlrev_b32_e32 v42, 11, v3
	v_mov_b32_e32 v43, v131
	s_waitcnt lgkmcnt(6)
	v_cvt_pk_bf16_f32 v14, v28, v26
	s_waitcnt lgkmcnt(4)
	v_cvt_pk_bf16_f32 v15, v30, v32
	s_waitcnt lgkmcnt(2)
	v_cvt_pk_bf16_f32 v16, v34, v36
	s_waitcnt lgkmcnt(0)
	v_cvt_pk_bf16_f32 v17, v38, v40
	v_lshl_add_u64 v[42:43], v[4:5], 0, v[42:43]
	v_or_b32_e32 v3, s8, v23
	global_store_dwordx4 v[42:43], v[14:17], off
	v_lshlrev_b32_e32 v26, 11, v3
	v_readlane_b32 s81, v249, 31
	v_cvt_pk_bf16_f32 v14, v29, v27
	v_mov_b32_e32 v27, v131
	v_cvt_pk_bf16_f32 v15, v31, v33
	v_cvt_pk_bf16_f32 v16, v35, v37
	v_cvt_pk_bf16_f32 v17, v39, v41
	v_lshl_add_u64 v[4:5], v[4:5], 0, v[26:27]
	global_store_dwordx4 v[4:5], v[14:17], off
	s_waitcnt lgkmcnt(0)
	v_readlane_b32 s82, v249, 32
	v_readlane_b32 s83, v249, 33
	s_branch .LBB0_124

.LBB0_124:
	s_andn2_b64 vcc, exec, s[18:19]
	s_cbranch_vccnz .LBB0_127
	s_mul_i32 s8, s11, 0x580000
	s_mul_hi_u32 s18, s10, 0x580000
	s_add_i32 s18, s18, s8
	s_mul_i32 s8, s10, 0x580000
	v_readlane_b32 s19, v249, 62
	s_add_u32 s8, s19, s8
	v_readlane_b32 s19, v249, 63
	v_readlane_b32 s68, v249, 34
	s_addc_u32 s18, s19, s18
	v_readlane_b32 s80, v249, 46
	v_readlane_b32 s81, v249, 47
	s_add_u32 s19, s80, s1
	s_addc_u32 s21, s81, s0
	s_lshl_b32 s0, s28, 1
	s_add_i32 s0, s0, 0x1ea00
	s_and_b32 s1, s0, 0x1ffc0
	s_lshl_b32 s0, s28, 5
	s_and_b32 s0, s0, 0x3e0
	s_lshl_b32 s20, s0, 2
	s_add_u32 s20, s19, s20
	v_or_b32_e32 v3, s1, v128
	s_addc_u32 s21, s21, 0
	v_lshl_add_u64 v[4:5], s[20:21], 0, v[130:131]
	v_lshlrev_b32_e32 v14, 12, v3
	v_mov_b32_e32 v15, v131
	v_lshl_add_u64 v[4:5], v[4:5], 0, v[14:15]
	s_movk_i32 s19, 0x2000
	v_add_co_u32_e32 v14, vcc, s19, v4
	global_load_dword v3, v[4:5], off nt
	s_nop 0
	v_addc_co_u32_e32 v15, vcc, 0, v5, vcc
	global_load_dword v13, v[14:15], off nt
	v_add_co_u32_e32 v14, vcc, s40, v4
	s_movk_i32 s19, 0x6000
	s_nop 0
	v_addc_co_u32_e32 v15, vcc, 0, v5, vcc
	global_load_dword v16, v[14:15], off nt
	v_add_co_u32_e32 v14, vcc, s19, v4
	s_mov_b32 s19, 0x8000
	s_nop 0
	v_addc_co_u32_e32 v15, vcc, 0, v5, vcc
	global_load_dword v17, v[14:15], off nt
	v_add_co_u32_e32 v14, vcc, s19, v4
	s_mov_b32 s19, 0xa000
	s_nop 0
	v_addc_co_u32_e32 v15, vcc, 0, v5, vcc
	global_load_dword v25, v[14:15], off nt
	v_add_co_u32_e32 v14, vcc, s19, v4
	s_mov_b32 s19, 0xc000
	s_nop 0
	v_addc_co_u32_e32 v15, vcc, 0, v5, vcc
	global_load_dword v26, v[14:15], off nt
	v_add_co_u32_e32 v14, vcc, s19, v4
	s_mov_b32 s19, 0xe000
	s_nop 0
	v_addc_co_u32_e32 v15, vcc, 0, v5, vcc
	global_load_dword v27, v[14:15], off nt
	v_add_co_u32_e32 v14, vcc, s19, v4
	s_mov_b32 s19, 0x14000
	s_nop 0
	v_addc_co_u32_e32 v15, vcc, 0, v5, vcc
	global_load_dword v28, v[14:15], off nt
	v_add_co_u32_e32 v14, vcc, s46, v4
	s_lshl_b32 s1, s1, 1
	s_nop 0
	v_addc_co_u32_e32 v15, vcc, 0, v5, vcc
	global_load_dword v29, v[14:15], off nt
	v_add_co_u32_e32 v14, vcc, s31, v4
	s_add_u32 s20, s8, s1
	s_nop 0
	v_addc_co_u32_e32 v15, vcc, 0, v5, vcc
	global_load_dword v30, v[14:15], off nt
	v_add_co_u32_e32 v14, vcc, s19, v4
	s_mov_b32 s19, 0x18000
	s_nop 0
	v_addc_co_u32_e32 v15, vcc, 0, v5, vcc
	global_load_dword v31, v[14:15], off nt
	v_add_co_u32_e32 v14, vcc, s48, v4
	s_addc_u32 s21, s18, 0
	s_nop 0
	v_addc_co_u32_e32 v15, vcc, 0, v5, vcc
	global_load_dword v32, v[14:15], off nt
	v_add_co_u32_e32 v14, vcc, s19, v4
	s_mov_b32 s19, 0x1a000
	s_nop 0
	v_addc_co_u32_e32 v15, vcc, 0, v5, vcc
	global_load_dword v33, v[14:15], off nt
	v_add_co_u32_e32 v14, vcc, s19, v4
	s_mov_b32 s19, 0x1c000
	s_nop 0
	v_addc_co_u32_e32 v15, vcc, 0, v5, vcc
	global_load_dword v34, v[14:15], off nt
	v_add_co_u32_e32 v14, vcc, s19, v4
	s_mov_b32 s19, 0x1e000
	s_nop 0
	v_addc_co_u32_e32 v15, vcc, 0, v5, vcc
	global_load_dword v35, v[14:15], off nt
	v_add_co_u32_e32 v14, vcc, s19, v4
	s_mov_b32 s19, 0x20000
	s_nop 0
	v_addc_co_u32_e32 v15, vcc, 0, v5, vcc
	global_load_dword v36, v[14:15], off nt
	v_add_co_u32_e32 v14, vcc, s19, v4
	v_readlane_b32 s69, v249, 35
	s_nop 0
	v_addc_co_u32_e32 v15, vcc, 0, v5, vcc
	global_load_dword v37, v[14:15], off nt
	v_add_co_u32_e32 v14, vcc, s54, v4
	v_readlane_b32 s70, v249, 36
	s_nop 0
	v_addc_co_u32_e32 v15, vcc, 0, v5, vcc
	global_load_dword v38, v[14:15], off nt
	v_add_co_u32_e32 v14, vcc, s35, v4
	v_readlane_b32 s71, v249, 37
	s_nop 0
	v_addc_co_u32_e32 v15, vcc, 0, v5, vcc
	global_load_dword v39, v[14:15], off nt
	v_add_co_u32_e32 v14, vcc, s55, v4
	v_readlane_b32 s72, v249, 38
	s_nop 0
	v_addc_co_u32_e32 v15, vcc, 0, v5, vcc
	global_load_dword v40, v[14:15], off nt
	v_add_co_u32_e32 v14, vcc, s56, v4
	v_readlane_b32 s73, v249, 39
	s_nop 0
	v_addc_co_u32_e32 v15, vcc, 0, v5, vcc
	global_load_dword v41, v[14:15], off nt
	v_add_co_u32_e32 v14, vcc, s57, v4
	v_readlane_b32 s74, v249, 40
	s_nop 0
	v_addc_co_u32_e32 v15, vcc, 0, v5, vcc
	global_load_dword v42, v[14:15], off nt
	v_add_co_u32_e32 v14, vcc, s58, v4
	v_readlane_b32 s75, v249, 41
	s_nop 0
	v_addc_co_u32_e32 v15, vcc, 0, v5, vcc
	global_load_dword v43, v[14:15], off nt
	v_add_co_u32_e32 v14, vcc, s59, v4
	v_readlane_b32 s76, v249, 42
	s_nop 0
	v_addc_co_u32_e32 v15, vcc, 0, v5, vcc
	global_load_dword v44, v[14:15], off nt
	v_add_co_u32_e32 v14, vcc, s60, v4
	v_readlane_b32 s77, v249, 43
	s_nop 0
	v_addc_co_u32_e32 v15, vcc, 0, v5, vcc
	global_load_dword v45, v[14:15], off nt
	v_add_co_u32_e32 v14, vcc, s61, v4
	v_readlane_b32 s78, v249, 44
	s_nop 0
	v_addc_co_u32_e32 v15, vcc, 0, v5, vcc
	global_load_dword v46, v[14:15], off nt
	v_add_co_u32_e32 v14, vcc, s62, v4
	v_readlane_b32 s79, v249, 45
	s_nop 0
	v_addc_co_u32_e32 v15, vcc, 0, v5, vcc
	global_load_dword v47, v[14:15], off nt
	v_add_co_u32_e32 v14, vcc, s37, v4
	v_readlane_b32 s82, v249, 48
	s_nop 0
	v_addc_co_u32_e32 v15, vcc, 0, v5, vcc
	global_load_dword v48, v[14:15], off nt
	v_add_co_u32_e32 v14, vcc, s63, v4
	v_readlane_b32 s83, v249, 49
	s_nop 0
	v_addc_co_u32_e32 v15, vcc, 0, v5, vcc
	global_load_dword v49, v[14:15], off nt
	v_add_co_u32_e32 v14, vcc, s64, v4
	s_nop 1
	v_addc_co_u32_e32 v15, vcc, 0, v5, vcc
	global_load_dword v50, v[14:15], off nt
	v_add_co_u32_e32 v14, vcc, s65, v4
	s_nop 1
	v_addc_co_u32_e32 v15, vcc, 0, v5, vcc
	v_add_co_u32_e32 v4, vcc, s66, v4
	global_load_dword v14, v[14:15], off nt
	s_nop 0
	v_addc_co_u32_e32 v5, vcc, 0, v5, vcc
	global_load_dword v4, v[4:5], off nt
	s_waitcnt vmcnt(30)
	ds_write2_b32 v18, v3, v13 offset1:66
	s_waitcnt vmcnt(28)
	ds_write2_b32 v18, v16, v17 offset0:132 offset1:198
	s_waitcnt vmcnt(26)
	ds_write2_b32 v12, v25, v26 offset0:8 offset1:74
	s_waitcnt vmcnt(24)
	ds_write2_b32 v12, v27, v28 offset0:140 offset1:206
	s_waitcnt vmcnt(22)
	ds_write2_b32 v11, v29, v30 offset0:16 offset1:82
	s_waitcnt vmcnt(20)
	ds_write2_b32 v11, v31, v32 offset0:148 offset1:214
	s_waitcnt vmcnt(18)
	ds_write2_b32 v10, v33, v34 offset0:24 offset1:90
	s_waitcnt vmcnt(16)
	ds_write2_b32 v10, v35, v36 offset0:156 offset1:222
	s_waitcnt vmcnt(14)
	ds_write2_b32 v9, v37, v38 offset0:32 offset1:98
	s_waitcnt vmcnt(12)
	ds_write2_b32 v9, v39, v40 offset0:164 offset1:230
	s_waitcnt vmcnt(10)
	ds_write2_b32 v8, v41, v42 offset0:40 offset1:106
	s_waitcnt vmcnt(8)
	ds_write2_b32 v8, v43, v44 offset0:172 offset1:238
	s_waitcnt vmcnt(6)
	ds_write2_b32 v7, v45, v46 offset0:48 offset1:114
	s_waitcnt vmcnt(4)
	ds_write2_b32 v7, v47, v48 offset0:180 offset1:246
	s_waitcnt vmcnt(2)
	ds_write2_b32 v6, v49, v50 offset0:56 offset1:122
	s_waitcnt vmcnt(0)
	ds_write2_b32 v6, v14, v4 offset0:188 offset1:254
	s_waitcnt lgkmcnt(0)
	ds_read2_b32 v[26:27], v20 offset0:33 offset1:41
	ds_read2_b32 v[28:29], v20 offset1:8
	ds_read2_b32 v[30:31], v20 offset0:66 offset1:74
	ds_read2_b32 v[32:33], v20 offset0:99 offset1:107
	ds_read2_b32 v[34:35], v20 offset0:132 offset1:140
	ds_read2_b32 v[36:37], v20 offset0:165 offset1:173
	ds_read2_b32 v[38:39], v20 offset0:198 offset1:206
	ds_read2_b32 v[40:41], v20 offset0:231 offset1:239
	v_mov_b32_e32 v3, v131
	v_lshl_add_u64 v[4:5], s[20:21], 0, v[2:3]
	v_or_b32_e32 v3, s0, v19
	v_mul_u32_u24_e32 v3, 0xb00, v3
	v_lshlrev_b32_e32 v42, 1, v3
	v_mov_b32_e32 v43, v131
	v_or_b32_e32 v3, s0, v21
	s_waitcnt lgkmcnt(6)
	v_cvt_pk_bf16_f32 v14, v28, v26
	s_waitcnt lgkmcnt(4)
	v_cvt_pk_bf16_f32 v15, v30, v32
	s_waitcnt lgkmcnt(2)
	v_cvt_pk_bf16_f32 v16, v34, v36
	s_waitcnt lgkmcnt(0)
	v_cvt_pk_bf16_f32 v17, v38, v40
	v_lshl_add_u64 v[42:43], v[4:5], 0, v[42:43]
	v_mul_u32_u24_e32 v3, 0xb00, v3
	global_store_dwordx4 v[42:43], v[14:17], off
	v_lshlrev_b32_e32 v26, 1, v3
	v_or_b32_e32 v3, s0, v22
	v_cvt_pk_bf16_f32 v14, v29, v27
	v_mov_b32_e32 v27, v131
	v_cvt_pk_bf16_f32 v15, v31, v33
	v_cvt_pk_bf16_f32 v16, v35, v37
	v_cvt_pk_bf16_f32 v17, v39, v41
	v_lshl_add_u64 v[26:27], v[4:5], 0, v[26:27]
	global_store_dwordx4 v[26:27], v[14:17], off
	ds_read2_b32 v[26:27], v20 offset0:16 offset1:24
	ds_read2_b32 v[28:29], v20 offset0:49 offset1:57
	ds_read2_b32 v[30:31], v20 offset0:82 offset1:90
	ds_read2_b32 v[32:33], v20 offset0:115 offset1:123
	ds_read2_b32 v[34:35], v20 offset0:148 offset1:156
	ds_read2_b32 v[36:37], v20 offset0:181 offset1:189
	ds_read2_b32 v[38:39], v20 offset0:214 offset1:222
	ds_read2_b32 v[40:41], v20 offset0:247 offset1:255
	v_mul_u32_u24_e32 v3, 0xb00, v3
	v_lshlrev_b32_e32 v42, 1, v3
	v_mov_b32_e32 v43, v131
	v_or_b32_e32 v3, s0, v23
	s_waitcnt lgkmcnt(6)
	v_cvt_pk_bf16_f32 v14, v26, v28
	s_waitcnt lgkmcnt(4)
	v_cvt_pk_bf16_f32 v15, v30, v32
	s_waitcnt lgkmcnt(2)
	v_cvt_pk_bf16_f32 v16, v34, v36
	s_waitcnt lgkmcnt(0)
	v_cvt_pk_bf16_f32 v17, v38, v40
	v_lshl_add_u64 v[42:43], v[4:5], 0, v[42:43]
	v_mul_u32_u24_e32 v3, 0xb00, v3
	global_store_dwordx4 v[42:43], v[14:17], off
	v_lshlrev_b32_e32 v26, 1, v3
	s_nop 0
	v_cvt_pk_bf16_f32 v14, v27, v29
	v_mov_b32_e32 v27, v131
	v_cvt_pk_bf16_f32 v15, v31, v33
	v_cvt_pk_bf16_f32 v16, v35, v37
	v_cvt_pk_bf16_f32 v17, v39, v41
	v_lshl_add_u64 v[4:5], v[4:5], 0, v[26:27]
	global_store_dwordx4 v[4:5], v[14:17], off
	s_waitcnt lgkmcnt(0)
	s_andn2_b64 vcc, exec, s[2:3]
	s_cbranch_vccz .LBB0_128

.LBB0_128:
	v_readlane_b32 s68, v249, 34
	s_lshl_b64 s[0:1], s[14:15], 2
	v_readlane_b32 s78, v249, 44
	v_readlane_b32 s79, v249, 45
	s_add_u32 s3, s78, s0
	s_addc_u32 s8, s79, s1
	s_add_i32 s0, s28, 0xfa80
	s_and_b32 s1, s0, 0xffff
	s_mul_i32 s1, s1, 0xba2f
	s_lshr_b32 s18, s1, 16
	s_lshr_b32 s1, s1, 22
	s_mulk_i32 s1, 0x58
	s_sub_i32 s0, s0, s1
	s_and_b32 s2, s0, 0xffff
	s_and_b32 s1, s18, 0xffc0
	s_lshl_b32 s0, s2, 5
	s_lshl_b32 s18, s2, 7
	v_or_b32_e32 v3, s1, v128
	s_add_u32 s18, s3, s18
	s_addc_u32 s19, s8, 0
	v_mul_u32_u24_e32 v3, 0xb00, v3
	v_lshl_add_u64 v[4:5], s[18:19], 0, v[130:131]
	v_lshlrev_b32_e32 v14, 2, v3
	v_mov_b32_e32 v15, v131
	v_lshl_add_u64 v[4:5], v[4:5], 0, v[14:15]
	v_add_co_u32_e32 v14, vcc, s67, v4
	global_load_dword v3, v[4:5], off nt
	s_nop 0
	v_addc_co_u32_e32 v15, vcc, 0, v5, vcc
	global_load_dword v13, v[14:15], off offset:2048 nt
	v_add_co_u32_e32 v14, vcc, s6, v4
	s_lshl_b32 s2, s2, 6
	s_nop 0
	v_addc_co_u32_e32 v15, vcc, 0, v5, vcc
	global_load_dword v16, v[14:15], off nt
	v_add_co_u32_e32 v14, vcc, s46, v4
	s_and_b32 s2, s2, 0x1f00
	s_nop 0
	v_addc_co_u32_e32 v15, vcc, 0, v5, vcc
	global_load_dword v17, v[14:15], off offset:2048 nt
	v_add_co_u32_e32 v14, vcc, s48, v4
	s_or_b32 s8, s2, 0x80
	s_nop 0
	v_addc_co_u32_e32 v15, vcc, 0, v5, vcc
	global_load_dword v25, v[14:15], off nt
	v_add_co_u32_e32 v14, vcc, s34, v4
	s_lshl_b32 s1, s1, 1
	s_nop 0
	v_addc_co_u32_e32 v15, vcc, 0, v5, vcc
	global_load_dword v26, v[14:15], off offset:2048 nt
	v_add_co_u32_e32 v14, vcc, s7, v4
	s_add_u32 s2, s12, s1
	s_nop 0
	v_addc_co_u32_e32 v15, vcc, 0, v5, vcc
	global_load_dword v27, v[14:15], off nt
	v_add_co_u32_e32 v14, vcc, s55, v4
	s_addc_u32 s3, s13, 0
	s_nop 0
	v_addc_co_u32_e32 v15, vcc, 0, v5, vcc
	global_load_dword v28, v[14:15], off offset:2048 nt
	v_add_co_u32_e32 v14, vcc, s58, v4
	s_and_b32 s0, s0, 0x60
	s_nop 0
	v_addc_co_u32_e32 v15, vcc, 0, v5, vcc
	global_load_dword v29, v[14:15], off nt
	v_add_co_u32_e32 v14, vcc, s4, v4
	v_readlane_b32 s69, v249, 35
	s_nop 0
	v_addc_co_u32_e32 v15, vcc, 0, v5, vcc
	global_load_dword v30, v[14:15], off offset:2048 nt
	v_add_co_u32_e32 v14, vcc, s5, v4
	v_readlane_b32 s70, v249, 36
	s_nop 0
	v_addc_co_u32_e32 v15, vcc, 0, v5, vcc
	global_load_dword v31, v[14:15], off nt
	v_add_co_u32_e32 v14, vcc, s65, v4
	v_readlane_b32 s71, v249, 37
	s_nop 0
	v_addc_co_u32_e32 v15, vcc, 0, v5, vcc
	global_load_dword v32, v[14:15], off offset:2048 nt
	v_add_co_u32_e32 v14, vcc, s39, v4
	v_readlane_b32 s72, v249, 38
	s_nop 0
	v_addc_co_u32_e32 v15, vcc, 0, v5, vcc
	global_load_dword v33, v[14:15], off nt
	v_add_co_u32_e32 v14, vcc, s41, v4
	v_readlane_b32 s73, v249, 39
	s_nop 0
	v_addc_co_u32_e32 v15, vcc, 0, v5, vcc
	global_load_dword v34, v[14:15], off offset:2048 nt
	v_add_co_u32_e32 v14, vcc, s42, v4
	v_readlane_b32 s74, v249, 40
	s_nop 0
	v_addc_co_u32_e32 v15, vcc, 0, v5, vcc
	global_load_dword v35, v[14:15], off nt
	v_add_co_u32_e32 v14, vcc, s43, v4
	v_readlane_b32 s75, v249, 41
	s_nop 0
	v_addc_co_u32_e32 v15, vcc, 0, v5, vcc
	global_load_dword v36, v[14:15], off offset:2048 nt
	v_add_co_u32_e32 v14, vcc, s44, v4
	v_readlane_b32 s76, v249, 42
	s_nop 0
	v_addc_co_u32_e32 v15, vcc, 0, v5, vcc
	global_load_dword v37, v[14:15], off nt
	v_add_co_u32_e32 v14, vcc, s45, v4
	v_readlane_b32 s77, v249, 43
	s_nop 0
	v_addc_co_u32_e32 v15, vcc, 0, v5, vcc
	global_load_dword v38, v[14:15], off offset:2048 nt
	v_add_co_u32_e32 v14, vcc, s47, v4
	v_readlane_b32 s80, v249, 46
	s_nop 0
	v_addc_co_u32_e32 v15, vcc, 0, v5, vcc
	global_load_dword v39, v[14:15], off nt
	v_add_co_u32_e32 v14, vcc, s49, v4
	v_readlane_b32 s81, v249, 47
	s_nop 0
	v_addc_co_u32_e32 v15, vcc, 0, v5, vcc
	global_load_dword v40, v[14:15], off offset:2048 nt
	v_add_co_u32_e32 v14, vcc, s50, v4
	v_readlane_b32 s82, v249, 48
	s_nop 0
	v_addc_co_u32_e32 v15, vcc, 0, v5, vcc
	global_load_dword v41, v[14:15], off nt
	v_add_co_u32_e32 v14, vcc, s51, v4
	v_readlane_b32 s83, v249, 49
	s_nop 0
	v_addc_co_u32_e32 v15, vcc, 0, v5, vcc
	global_load_dword v42, v[14:15], off offset:2048 nt
	v_add_co_u32_e32 v14, vcc, s52, v4
	s_nop 1
	v_addc_co_u32_e32 v15, vcc, 0, v5, vcc
	global_load_dword v43, v[14:15], off nt
	v_add_co_u32_e32 v14, vcc, s53, v4
	s_nop 1
	v_addc_co_u32_e32 v15, vcc, 0, v5, vcc
	global_load_dword v44, v[14:15], off offset:2048 nt
	v_add_co_u32_e32 v14, vcc, s84, v4
	s_nop 1
	v_addc_co_u32_e32 v15, vcc, 0, v5, vcc
	global_load_dword v45, v[14:15], off nt
	v_add_co_u32_e32 v14, vcc, s85, v4
	s_nop 1
	v_addc_co_u32_e32 v15, vcc, 0, v5, vcc
	global_load_dword v46, v[14:15], off offset:2048 nt
	v_add_co_u32_e32 v14, vcc, s86, v4
	s_nop 1
	v_addc_co_u32_e32 v15, vcc, 0, v5, vcc
	global_load_dword v47, v[14:15], off nt
	v_add_co_u32_e32 v14, vcc, s87, v4
	s_nop 1
	v_addc_co_u32_e32 v15, vcc, 0, v5, vcc
	global_load_dword v48, v[14:15], off offset:2048 nt
	v_add_co_u32_e32 v14, vcc, s88, v4
	s_nop 1
	v_addc_co_u32_e32 v15, vcc, 0, v5, vcc
	global_load_dword v49, v[14:15], off nt
	v_add_co_u32_e32 v14, vcc, s89, v4
	s_nop 1
	v_addc_co_u32_e32 v15, vcc, 0, v5, vcc
	global_load_dword v50, v[14:15], off offset:2048 nt
	v_add_co_u32_e32 v14, vcc, s90, v4
	s_nop 1
	v_addc_co_u32_e32 v15, vcc, 0, v5, vcc
	v_add_co_u32_e32 v4, vcc, s91, v4
	global_load_dword v14, v[14:15], off nt
	s_nop 0
	v_addc_co_u32_e32 v5, vcc, 0, v5, vcc
	global_load_dword v4, v[4:5], off offset:2048 nt
	s_waitcnt vmcnt(30)
	ds_write2_b32 v18, v3, v13 offset1:66
	s_waitcnt vmcnt(28)
	ds_write2_b32 v18, v16, v17 offset0:132 offset1:198
	s_waitcnt vmcnt(26)
	ds_write2_b32 v12, v25, v26 offset0:8 offset1:74
	s_waitcnt vmcnt(24)
	ds_write2_b32 v12, v27, v28 offset0:140 offset1:206
	s_waitcnt vmcnt(22)
	ds_write2_b32 v11, v29, v30 offset0:16 offset1:82
	s_waitcnt vmcnt(20)
	ds_write2_b32 v11, v31, v32 offset0:148 offset1:214
	s_waitcnt vmcnt(18)
	ds_write2_b32 v10, v33, v34 offset0:24 offset1:90
	s_waitcnt vmcnt(16)
	ds_write2_b32 v10, v35, v36 offset0:156 offset1:222
	s_waitcnt vmcnt(14)
	ds_write2_b32 v9, v37, v38 offset0:32 offset1:98
	s_waitcnt vmcnt(12)
	ds_write2_b32 v9, v39, v40 offset0:164 offset1:230
	s_waitcnt vmcnt(10)
	ds_write2_b32 v8, v41, v42 offset0:40 offset1:106
	s_waitcnt vmcnt(8)
	ds_write2_b32 v8, v43, v44 offset0:172 offset1:238
	s_waitcnt vmcnt(6)
	ds_write2_b32 v7, v45, v46 offset0:48 offset1:114
	s_waitcnt vmcnt(4)
	ds_write2_b32 v7, v47, v48 offset0:180 offset1:246
	s_waitcnt vmcnt(2)
	ds_write2_b32 v6, v49, v50 offset0:56 offset1:122
	s_waitcnt vmcnt(0)
	ds_write2_b32 v6, v14, v4 offset0:188 offset1:254
	s_waitcnt lgkmcnt(0)
	ds_read2_b32 v[26:27], v20 offset0:33 offset1:41
	ds_read2_b32 v[28:29], v20 offset1:8
	ds_read2_b32 v[30:31], v20 offset0:66 offset1:74
	ds_read2_b32 v[32:33], v20 offset0:99 offset1:107
	ds_read2_b32 v[34:35], v20 offset0:132 offset1:140
	ds_read2_b32 v[36:37], v20 offset0:165 offset1:173
	ds_read2_b32 v[38:39], v20 offset0:198 offset1:206
	ds_read2_b32 v[40:41], v20 offset0:231 offset1:239
	v_mov_b32_e32 v3, v131
	v_lshl_add_u64 v[4:5], s[2:3], 0, v[2:3]
	v_or_b32_e32 v3, s0, v19
	v_or_b32_e32 v3, s8, v3
	v_lshlrev_b32_e32 v42, 11, v3
	v_mov_b32_e32 v43, v131
	v_or_b32_e32 v3, s0, v21
	s_waitcnt lgkmcnt(6)
	v_cvt_pk_bf16_f32 v14, v28, v26
	s_waitcnt lgkmcnt(4)
	v_cvt_pk_bf16_f32 v15, v30, v32
	s_waitcnt lgkmcnt(2)
	v_cvt_pk_bf16_f32 v16, v34, v36
	s_waitcnt lgkmcnt(0)
	v_cvt_pk_bf16_f32 v17, v38, v40
	v_lshl_add_u64 v[42:43], v[4:5], 0, v[42:43]
	v_or_b32_e32 v3, s8, v3
	global_store_dwordx4 v[42:43], v[14:17], off
	v_lshlrev_b32_e32 v26, 11, v3
	v_or_b32_e32 v3, s0, v22
	v_cvt_pk_bf16_f32 v14, v29, v27
	v_mov_b32_e32 v27, v131
	v_cvt_pk_bf16_f32 v15, v31, v33
	v_cvt_pk_bf16_f32 v16, v35, v37
	v_cvt_pk_bf16_f32 v17, v39, v41
	v_lshl_add_u64 v[26:27], v[4:5], 0, v[26:27]
	global_store_dwordx4 v[26:27], v[14:17], off
	ds_read2_b32 v[26:27], v20 offset0:49 offset1:57
	ds_read2_b32 v[28:29], v20 offset0:16 offset1:24
	ds_read2_b32 v[30:31], v20 offset0:82 offset1:90
	ds_read2_b32 v[32:33], v20 offset0:115 offset1:123
	ds_read2_b32 v[34:35], v20 offset0:148 offset1:156
	ds_read2_b32 v[36:37], v20 offset0:181 offset1:189
	ds_read2_b32 v[38:39], v20 offset0:214 offset1:222
	ds_read2_b32 v[40:41], v20 offset0:247 offset1:255
	v_or_b32_e32 v3, s8, v3
	v_lshlrev_b32_e32 v42, 11, v3
	v_mov_b32_e32 v43, v131
	v_or_b32_e32 v3, s0, v23
	s_waitcnt lgkmcnt(6)
	v_cvt_pk_bf16_f32 v14, v28, v26
	s_waitcnt lgkmcnt(4)
	v_cvt_pk_bf16_f32 v15, v30, v32
	s_waitcnt lgkmcnt(2)
	v_cvt_pk_bf16_f32 v16, v34, v36
	s_waitcnt lgkmcnt(0)
	v_cvt_pk_bf16_f32 v17, v38, v40
	v_lshl_add_u64 v[42:43], v[4:5], 0, v[42:43]
	v_or_b32_e32 v3, s8, v3
	global_store_dwordx4 v[42:43], v[14:17], off
	v_lshlrev_b32_e32 v26, 11, v3
	s_nop 0
	v_cvt_pk_bf16_f32 v14, v29, v27
	v_mov_b32_e32 v27, v131
	v_cvt_pk_bf16_f32 v15, v31, v33
	v_cvt_pk_bf16_f32 v16, v35, v37
	v_cvt_pk_bf16_f32 v17, v39, v41
	v_lshl_add_u64 v[4:5], v[4:5], 0, v[26:27]
	global_store_dwordx4 v[4:5], v[14:17], off
	s_waitcnt lgkmcnt(0)
	s_andn2_b64 vcc, exec, s[16:17]
	s_cbranch_vccnz .LBB0_97
.LBB0_129:
	v_readlane_b32 s68, v249, 34
	s_lshl_b64 s[0:1], s[14:15], 2
	v_readlane_b32 s76, v249, 42
	v_readlane_b32 s77, v249, 43
	s_add_u32 s3, s76, s0
	s_addc_u32 s8, s77, s1
	s_and_b32 s0, s28, 0xffff
	s_mul_i32 s0, s0, 0xba2f
	s_lshr_b32 s1, s0, 16
	s_lshr_b32 s0, s0, 22
	s_mulk_i32 s0, 0x58
	s_sub_i32 s0, s28, s0
	s_and_b32 s2, s0, 0xffff
	s_and_b32 s1, s1, 0xffc0
	s_lshl_b32 s0, s2, 5
	s_lshl_b32 s14, s2, 7
	v_or_b32_e32 v3, s1, v128
	s_add_u32 s14, s3, s14
	s_addc_u32 s15, s8, 0
	v_mul_u32_u24_e32 v3, 0xb00, v3
	v_lshl_add_u64 v[4:5], s[14:15], 0, v[130:131]
	v_lshlrev_b32_e32 v14, 2, v3
	v_mov_b32_e32 v15, v131
	v_lshl_add_u64 v[4:5], v[4:5], 0, v[14:15]
	v_add_co_u32_e32 v14, vcc, s67, v4
	global_load_dword v3, v[4:5], off nt
	s_nop 0
	v_addc_co_u32_e32 v15, vcc, 0, v5, vcc
	global_load_dword v13, v[14:15], off offset:2048 nt
	v_add_co_u32_e32 v14, vcc, s6, v4
	s_lshl_b32 s2, s2, 6
	s_nop 0
	v_addc_co_u32_e32 v15, vcc, 0, v5, vcc
	global_load_dword v16, v[14:15], off nt
	v_add_co_u32_e32 v14, vcc, s46, v4
	s_and_b32 s8, s2, 0x1f00
	s_nop 0
	v_addc_co_u32_e32 v15, vcc, 0, v5, vcc
	global_load_dword v17, v[14:15], off offset:2048 nt
	v_add_co_u32_e32 v14, vcc, s48, v4
	s_lshl_b32 s1, s1, 1
	s_nop 0
	v_addc_co_u32_e32 v15, vcc, 0, v5, vcc
	global_load_dword v25, v[14:15], off nt
	v_add_co_u32_e32 v14, vcc, s34, v4
	s_add_u32 s2, s12, s1
	s_nop 0
	v_addc_co_u32_e32 v15, vcc, 0, v5, vcc
	global_load_dword v26, v[14:15], off offset:2048 nt
	v_add_co_u32_e32 v14, vcc, s7, v4
	s_addc_u32 s3, s13, 0
	s_nop 0
	v_addc_co_u32_e32 v15, vcc, 0, v5, vcc
	global_load_dword v27, v[14:15], off nt
	v_add_co_u32_e32 v14, vcc, s55, v4
	s_and_b32 s0, s0, 0x60
	s_nop 0
	v_addc_co_u32_e32 v15, vcc, 0, v5, vcc
	global_load_dword v28, v[14:15], off offset:2048 nt
	v_add_co_u32_e32 v14, vcc, s58, v4
	s_or_b32 s0, s8, s0
	s_nop 0
	v_addc_co_u32_e32 v15, vcc, 0, v5, vcc
	global_load_dword v29, v[14:15], off nt
	v_add_co_u32_e32 v14, vcc, s4, v4
	v_readlane_b32 s69, v249, 35
	s_nop 0
	v_addc_co_u32_e32 v15, vcc, 0, v5, vcc
	global_load_dword v30, v[14:15], off offset:2048 nt
	v_add_co_u32_e32 v14, vcc, s5, v4
	v_readlane_b32 s70, v249, 36
	s_nop 0
	v_addc_co_u32_e32 v15, vcc, 0, v5, vcc
	global_load_dword v31, v[14:15], off nt
	v_add_co_u32_e32 v14, vcc, s65, v4
	v_readlane_b32 s71, v249, 37
	s_nop 0
	v_addc_co_u32_e32 v15, vcc, 0, v5, vcc
	global_load_dword v32, v[14:15], off offset:2048 nt
	v_add_co_u32_e32 v14, vcc, s39, v4
	v_readlane_b32 s72, v249, 38
	s_nop 0
	v_addc_co_u32_e32 v15, vcc, 0, v5, vcc
	global_load_dword v33, v[14:15], off nt
	v_add_co_u32_e32 v14, vcc, s41, v4
	v_readlane_b32 s73, v249, 39
	s_nop 0
	v_addc_co_u32_e32 v15, vcc, 0, v5, vcc
	global_load_dword v34, v[14:15], off offset:2048 nt
	v_add_co_u32_e32 v14, vcc, s42, v4
	v_readlane_b32 s74, v249, 40
	s_nop 0
	v_addc_co_u32_e32 v15, vcc, 0, v5, vcc
	global_load_dword v35, v[14:15], off nt
	v_add_co_u32_e32 v14, vcc, s43, v4
	v_readlane_b32 s75, v249, 41
	s_nop 0
	v_addc_co_u32_e32 v15, vcc, 0, v5, vcc
	global_load_dword v36, v[14:15], off offset:2048 nt
	v_add_co_u32_e32 v14, vcc, s44, v4
	v_readlane_b32 s78, v249, 44
	s_nop 0
	v_addc_co_u32_e32 v15, vcc, 0, v5, vcc
	global_load_dword v37, v[14:15], off nt
	v_add_co_u32_e32 v14, vcc, s45, v4
	v_readlane_b32 s79, v249, 45
	s_nop 0
	v_addc_co_u32_e32 v15, vcc, 0, v5, vcc
	global_load_dword v38, v[14:15], off offset:2048 nt
	v_add_co_u32_e32 v14, vcc, s47, v4
	v_readlane_b32 s80, v249, 46
	s_nop 0
	v_addc_co_u32_e32 v15, vcc, 0, v5, vcc
	global_load_dword v39, v[14:15], off nt
	v_add_co_u32_e32 v14, vcc, s49, v4
	v_readlane_b32 s81, v249, 47
	s_nop 0
	v_addc_co_u32_e32 v15, vcc, 0, v5, vcc
	global_load_dword v40, v[14:15], off offset:2048 nt
	v_add_co_u32_e32 v14, vcc, s50, v4
	v_readlane_b32 s82, v249, 48
	s_nop 0
	v_addc_co_u32_e32 v15, vcc, 0, v5, vcc
	global_load_dword v41, v[14:15], off nt
	v_add_co_u32_e32 v14, vcc, s51, v4
	v_readlane_b32 s83, v249, 49
	s_nop 0
	v_addc_co_u32_e32 v15, vcc, 0, v5, vcc
	global_load_dword v42, v[14:15], off offset:2048 nt
	v_add_co_u32_e32 v14, vcc, s52, v4
	s_nop 1
	v_addc_co_u32_e32 v15, vcc, 0, v5, vcc
	global_load_dword v43, v[14:15], off nt
	v_add_co_u32_e32 v14, vcc, s53, v4
	s_nop 1
	v_addc_co_u32_e32 v15, vcc, 0, v5, vcc
	global_load_dword v44, v[14:15], off offset:2048 nt
	v_add_co_u32_e32 v14, vcc, s84, v4
	s_nop 1
	v_addc_co_u32_e32 v15, vcc, 0, v5, vcc
	global_load_dword v45, v[14:15], off nt
	v_add_co_u32_e32 v14, vcc, s85, v4
	s_nop 1
	v_addc_co_u32_e32 v15, vcc, 0, v5, vcc
	global_load_dword v46, v[14:15], off offset:2048 nt
	v_add_co_u32_e32 v14, vcc, s86, v4
	s_nop 1
	v_addc_co_u32_e32 v15, vcc, 0, v5, vcc
	global_load_dword v47, v[14:15], off nt
	v_add_co_u32_e32 v14, vcc, s87, v4
	s_nop 1
	v_addc_co_u32_e32 v15, vcc, 0, v5, vcc
	global_load_dword v48, v[14:15], off offset:2048 nt
	v_add_co_u32_e32 v14, vcc, s88, v4
	s_nop 1
	v_addc_co_u32_e32 v15, vcc, 0, v5, vcc
	global_load_dword v49, v[14:15], off nt
	v_add_co_u32_e32 v14, vcc, s89, v4
	s_nop 1
	v_addc_co_u32_e32 v15, vcc, 0, v5, vcc
	global_load_dword v50, v[14:15], off offset:2048 nt
	v_add_co_u32_e32 v14, vcc, s90, v4
	s_nop 1
	v_addc_co_u32_e32 v15, vcc, 0, v5, vcc
	v_add_co_u32_e32 v4, vcc, s91, v4
	global_load_dword v14, v[14:15], off nt
	s_nop 0
	v_addc_co_u32_e32 v5, vcc, 0, v5, vcc
	global_load_dword v4, v[4:5], off offset:2048 nt
	s_waitcnt vmcnt(30)
	ds_write2_b32 v18, v3, v13 offset1:66
	s_waitcnt vmcnt(28)
	ds_write2_b32 v18, v16, v17 offset0:132 offset1:198
	s_waitcnt vmcnt(26)
	ds_write2_b32 v12, v25, v26 offset0:8 offset1:74
	s_waitcnt vmcnt(24)
	ds_write2_b32 v12, v27, v28 offset0:140 offset1:206
	s_waitcnt vmcnt(22)
	ds_write2_b32 v11, v29, v30 offset0:16 offset1:82
	s_waitcnt vmcnt(20)
	ds_write2_b32 v11, v31, v32 offset0:148 offset1:214
	s_waitcnt vmcnt(18)
	ds_write2_b32 v10, v33, v34 offset0:24 offset1:90
	s_waitcnt vmcnt(16)
	ds_write2_b32 v10, v35, v36 offset0:156 offset1:222
	s_waitcnt vmcnt(14)
	ds_write2_b32 v9, v37, v38 offset0:32 offset1:98
	s_waitcnt vmcnt(12)
	ds_write2_b32 v9, v39, v40 offset0:164 offset1:230
	s_waitcnt vmcnt(10)
	ds_write2_b32 v8, v41, v42 offset0:40 offset1:106
	s_waitcnt vmcnt(8)
	ds_write2_b32 v8, v43, v44 offset0:172 offset1:238
	s_waitcnt vmcnt(6)
	ds_write2_b32 v7, v45, v46 offset0:48 offset1:114
	s_waitcnt vmcnt(4)
	ds_write2_b32 v7, v47, v48 offset0:180 offset1:246
	s_waitcnt vmcnt(2)
	ds_write2_b32 v6, v49, v50 offset0:56 offset1:122
	s_waitcnt vmcnt(0)
	ds_write2_b32 v6, v14, v4 offset0:188 offset1:254
	s_waitcnt lgkmcnt(0)
	ds_read2_b32 v[8:9], v20 offset0:33 offset1:41
	ds_read2_b32 v[10:11], v20 offset1:8
	ds_read2_b32 v[12:13], v20 offset0:66 offset1:74
	ds_read2_b32 v[14:15], v20 offset0:99 offset1:107
	ds_read2_b32 v[16:17], v20 offset0:132 offset1:140
	ds_read2_b32 v[26:27], v20 offset0:165 offset1:173
	ds_read2_b32 v[28:29], v20 offset0:198 offset1:206
	ds_read2_b32 v[30:31], v20 offset0:231 offset1:239
	v_mov_b32_e32 v3, v131
	v_lshl_add_u64 v[6:7], s[2:3], 0, v[2:3]
	s_waitcnt lgkmcnt(6)
	v_cvt_pk_bf16_f32 v2, v10, v8
	v_or_b32_e32 v8, s0, v19
	v_lshlrev_b32_e32 v32, 11, v8
	v_mov_b32_e32 v33, v131
	s_waitcnt lgkmcnt(4)
	v_cvt_pk_bf16_f32 v3, v12, v14
	s_waitcnt lgkmcnt(2)
	v_cvt_pk_bf16_f32 v4, v16, v26
	s_waitcnt lgkmcnt(0)
	v_cvt_pk_bf16_f32 v5, v28, v30
	v_lshl_add_u64 v[32:33], v[6:7], 0, v[32:33]
	v_or_b32_e32 v8, s0, v21
	global_store_dwordx4 v[32:33], v[2:5], off
	v_lshlrev_b32_e32 v8, 11, v8
	v_mov_b32_e32 v33, v131
	v_cvt_pk_bf16_f32 v2, v11, v9
	v_mov_b32_e32 v9, v131
	v_cvt_pk_bf16_f32 v3, v13, v15
	v_cvt_pk_bf16_f32 v4, v17, v27
	v_cvt_pk_bf16_f32 v5, v29, v31
	v_lshl_add_u64 v[8:9], v[6:7], 0, v[8:9]
	global_store_dwordx4 v[8:9], v[2:5], off
	ds_read2_b32 v[8:9], v20 offset0:49 offset1:57
	ds_read2_b32 v[10:11], v20 offset0:16 offset1:24
	ds_read2_b32 v[12:13], v20 offset0:82 offset1:90
	ds_read2_b32 v[14:15], v20 offset0:115 offset1:123
	ds_read2_b32 v[16:17], v20 offset0:148 offset1:156
	ds_read2_b32 v[26:27], v20 offset0:181 offset1:189
	ds_read2_b32 v[28:29], v20 offset0:214 offset1:222
	ds_read2_b32 v[30:31], v20 offset0:247 offset1:255
	s_waitcnt lgkmcnt(6)
	v_cvt_pk_bf16_f32 v2, v10, v8
	v_or_b32_e32 v8, s0, v22
	v_lshlrev_b32_e32 v32, 11, v8
	s_waitcnt lgkmcnt(4)
	v_cvt_pk_bf16_f32 v3, v12, v14
	s_waitcnt lgkmcnt(2)
	v_cvt_pk_bf16_f32 v4, v16, v26
	s_waitcnt lgkmcnt(0)
	v_cvt_pk_bf16_f32 v5, v28, v30
	v_lshl_add_u64 v[32:33], v[6:7], 0, v[32:33]
	v_or_b32_e32 v8, s0, v23
	global_store_dwordx4 v[32:33], v[2:5], off
	v_lshlrev_b32_e32 v8, 11, v8
	s_nop 0
	v_cvt_pk_bf16_f32 v2, v11, v9
	v_mov_b32_e32 v9, v131
	v_cvt_pk_bf16_f32 v3, v13, v15
	v_cvt_pk_bf16_f32 v4, v17, v27
	v_cvt_pk_bf16_f32 v5, v29, v31
	v_lshl_add_u64 v[6:7], v[6:7], 0, v[8:9]
	global_store_dwordx4 v[6:7], v[2:5], off
	s_waitcnt lgkmcnt(0)
	s_branch .LBB0_97
